# softmax max folded into the QK MFMA accumulator input (bias block = -m), q up-projection pre-scaled by scale*log2e in f32 before its bf16 rounding: no per-score fma, no per-block threshold math
# speedup vs baseline: 1.0328x; 1.0091x over previous
.LBB0_1269:
	v_lshl_or_b32 v146, s64, 8, v150
	v_lshl_add_u32 v156, s63, 8, v148
	v_ashrrev_i32_e32 v147, 31, v146
	v_mov_b64_e32 v[144:145], s[58:59]
	v_mad_i64_i32 v[154:155], s[16:17], v156, s62, v[144:145]
	v_lshlrev_b64 v[146:147], 1, v[146:147]
	v_lshl_add_u64 v[154:155], v[154:155], 0, v[146:147]
	v_mul_f32_e32 v124, 0x3dd53b94, v124
	v_mul_f32_e32 v125, 0x3dd53b94, v125
	v_cvt_pk_bf16_f32 v124, v124, v125
	v_mul_f32_e32 v126, 0x3dd53b94, v126
	v_mul_f32_e32 v127, 0x3dd53b94, v127
	v_cvt_pk_bf16_f32 v125, v126, v127
	v_mul_f32_e32 v120, 0x3dd53b94, v120
	v_mul_f32_e32 v121, 0x3dd53b94, v121
	v_cvt_pk_bf16_f32 v126, v120, v121
	v_mul_f32_e32 v122, 0x3dd53b94, v122
	v_mul_f32_e32 v123, 0x3dd53b94, v123
	v_cvt_pk_bf16_f32 v127, v122, v123
	global_store_dwordx4 v[154:155], v[124:127], off
	v_mul_f32_e32 v112, 0x3dd53b94, v112
	v_mul_f32_e32 v113, 0x3dd53b94, v113
	v_cvt_pk_bf16_f32 v112, v112, v113
	v_mul_f32_e32 v114, 0x3dd53b94, v114
	v_mul_f32_e32 v115, 0x3dd53b94, v115
	v_cvt_pk_bf16_f32 v113, v114, v115
	v_mul_f32_e32 v104, 0x3dd53b94, v104
	v_mul_f32_e32 v105, 0x3dd53b94, v105
	v_cvt_pk_bf16_f32 v114, v104, v105
	v_or_b32_e32 v104, 16, v156
	v_mad_i64_i32 v[104:105], s[16:17], v104, s62, v[144:145]
	v_mul_f32_e32 v106, 0x3dd53b94, v106
	v_mul_f32_e32 v107, 0x3dd53b94, v107
	v_cvt_pk_bf16_f32 v115, v106, v107
	global_store_dwordx4 v[154:155], v[112:115], off offset:256
	s_and_b64 vcc, exec, s[0:1]
	s_mov_b64 s[0:1], -1
	v_lshl_add_u64 v[112:113], v[104:105], 0, v[146:147]
	v_mul_f32_e32 v116, 0x3dd53b94, v116
	v_mul_f32_e32 v117, 0x3dd53b94, v117
	v_cvt_pk_bf16_f32 v104, v116, v117
	v_mul_f32_e32 v118, 0x3dd53b94, v118
	v_mul_f32_e32 v119, 0x3dd53b94, v119
	v_cvt_pk_bf16_f32 v105, v118, v119
	v_mul_f32_e32 v108, 0x3dd53b94, v108
	v_mul_f32_e32 v109, 0x3dd53b94, v109
	v_cvt_pk_bf16_f32 v106, v108, v109
	v_mul_f32_e32 v110, 0x3dd53b94, v110
	v_mul_f32_e32 v111, 0x3dd53b94, v111
	v_cvt_pk_bf16_f32 v107, v110, v111
	global_store_dwordx4 v[112:113], v[104:107], off
	v_mul_f32_e32 v96, 0x3dd53b94, v96
	v_mul_f32_e32 v97, 0x3dd53b94, v97
	v_cvt_pk_bf16_f32 v96, v96, v97
	v_mul_f32_e32 v98, 0x3dd53b94, v98
	v_mul_f32_e32 v99, 0x3dd53b94, v99
	v_cvt_pk_bf16_f32 v97, v98, v99
	v_mul_f32_e32 v88, 0x3dd53b94, v88
	v_mul_f32_e32 v89, 0x3dd53b94, v89
	v_cvt_pk_bf16_f32 v98, v88, v89
	v_or_b32_e32 v88, 32, v156
	v_mad_i64_i32 v[88:89], s[16:17], v88, s62, v[144:145]
	v_mul_f32_e32 v90, 0x3dd53b94, v90
	v_mul_f32_e32 v91, 0x3dd53b94, v91
	v_cvt_pk_bf16_f32 v99, v90, v91
	global_store_dwordx4 v[112:113], v[96:99], off offset:256
	s_nop 1
	v_lshl_add_u64 v[96:97], v[88:89], 0, v[146:147]
	v_mul_f32_e32 v100, 0x3dd53b94, v100
	v_mul_f32_e32 v101, 0x3dd53b94, v101
	v_cvt_pk_bf16_f32 v88, v100, v101
	v_mul_f32_e32 v102, 0x3dd53b94, v102
	v_mul_f32_e32 v103, 0x3dd53b94, v103
	v_cvt_pk_bf16_f32 v89, v102, v103
	v_mul_f32_e32 v92, 0x3dd53b94, v92
	v_mul_f32_e32 v93, 0x3dd53b94, v93
	v_cvt_pk_bf16_f32 v90, v92, v93
	v_mul_f32_e32 v94, 0x3dd53b94, v94
	v_mul_f32_e32 v95, 0x3dd53b94, v95
	v_cvt_pk_bf16_f32 v91, v94, v95
	global_store_dwordx4 v[96:97], v[88:91], off
	v_mul_f32_e32 v80, 0x3dd53b94, v80
	v_mul_f32_e32 v81, 0x3dd53b94, v81
	v_cvt_pk_bf16_f32 v80, v80, v81
	v_mul_f32_e32 v82, 0x3dd53b94, v82
	v_mul_f32_e32 v83, 0x3dd53b94, v83
	v_cvt_pk_bf16_f32 v81, v82, v83
	v_mul_f32_e32 v72, 0x3dd53b94, v72
	v_mul_f32_e32 v73, 0x3dd53b94, v73
	v_cvt_pk_bf16_f32 v82, v72, v73
	v_or_b32_e32 v72, 48, v156
	v_mad_i64_i32 v[72:73], s[16:17], v72, s62, v[144:145]
	v_mul_f32_e32 v74, 0x3dd53b94, v74
	v_mul_f32_e32 v75, 0x3dd53b94, v75
	v_cvt_pk_bf16_f32 v83, v74, v75
	global_store_dwordx4 v[96:97], v[80:83], off offset:256
	s_nop 1
	v_lshl_add_u64 v[80:81], v[72:73], 0, v[146:147]
	v_mul_f32_e32 v84, 0x3dd53b94, v84
	v_mul_f32_e32 v85, 0x3dd53b94, v85
	v_cvt_pk_bf16_f32 v72, v84, v85
	v_mul_f32_e32 v86, 0x3dd53b94, v86
	v_mul_f32_e32 v87, 0x3dd53b94, v87
	v_cvt_pk_bf16_f32 v73, v86, v87
	v_mul_f32_e32 v76, 0x3dd53b94, v76
	v_mul_f32_e32 v77, 0x3dd53b94, v77
	v_cvt_pk_bf16_f32 v74, v76, v77
	v_mul_f32_e32 v78, 0x3dd53b94, v78
	v_mul_f32_e32 v79, 0x3dd53b94, v79
	v_cvt_pk_bf16_f32 v75, v78, v79
	global_store_dwordx4 v[80:81], v[72:75], off
	v_mul_f32_e32 v68, 0x3dd53b94, v68
	v_mul_f32_e32 v69, 0x3dd53b94, v69
	v_cvt_pk_bf16_f32 v68, v68, v69
	v_mul_f32_e32 v70, 0x3dd53b94, v70
	v_mul_f32_e32 v71, 0x3dd53b94, v71
	v_cvt_pk_bf16_f32 v69, v70, v71
	v_mul_f32_e32 v64, 0x3dd53b94, v64
	v_mul_f32_e32 v65, 0x3dd53b94, v65
	v_cvt_pk_bf16_f32 v70, v64, v65
	v_add_u32_e32 v64, 0x80, v156
	v_mad_i64_i32 v[64:65], s[16:17], v64, s62, v[144:145]
	v_lshl_add_u64 v[64:65], v[64:65], 0, v[146:147]
	v_mul_f32_e32 v66, 0x3dd53b94, v66
	v_mul_f32_e32 v67, 0x3dd53b94, v67
	v_cvt_pk_bf16_f32 v71, v66, v67
	global_store_dwordx4 v[80:81], v[68:71], off offset:256
	v_mul_f32_e32 v60, 0x3dd53b94, v60
	v_mul_f32_e32 v61, 0x3dd53b94, v61
	v_cvt_pk_bf16_f32 v60, v60, v61
	v_mul_f32_e32 v62, 0x3dd53b94, v62
	v_mul_f32_e32 v63, 0x3dd53b94, v63
	v_cvt_pk_bf16_f32 v61, v62, v63
	v_mul_f32_e32 v56, 0x3dd53b94, v56
	v_mul_f32_e32 v57, 0x3dd53b94, v57
	v_cvt_pk_bf16_f32 v62, v56, v57
	v_mul_f32_e32 v58, 0x3dd53b94, v58
	v_mul_f32_e32 v59, 0x3dd53b94, v59
	v_cvt_pk_bf16_f32 v63, v58, v59
	global_store_dwordx4 v[64:65], v[60:63], off
	v_mul_f32_e32 v48, 0x3dd53b94, v48
	v_mul_f32_e32 v49, 0x3dd53b94, v49
	v_cvt_pk_bf16_f32 v48, v48, v49
	v_mul_f32_e32 v50, 0x3dd53b94, v50
	v_mul_f32_e32 v51, 0x3dd53b94, v51
	v_cvt_pk_bf16_f32 v49, v50, v51
	v_mul_f32_e32 v40, 0x3dd53b94, v40
	v_mul_f32_e32 v41, 0x3dd53b94, v41
	v_cvt_pk_bf16_f32 v50, v40, v41
	v_add_u32_e32 v40, 0x90, v156
	v_mad_i64_i32 v[40:41], s[16:17], v40, s62, v[144:145]
	v_mul_f32_e32 v42, 0x3dd53b94, v42
	v_mul_f32_e32 v43, 0x3dd53b94, v43
	v_cvt_pk_bf16_f32 v51, v42, v43
	global_store_dwordx4 v[64:65], v[48:51], off offset:256
	s_nop 1
	v_lshl_add_u64 v[48:49], v[40:41], 0, v[146:147]
	v_mul_f32_e32 v52, 0x3dd53b94, v52
	v_mul_f32_e32 v53, 0x3dd53b94, v53
	v_cvt_pk_bf16_f32 v40, v52, v53
	v_mul_f32_e32 v54, 0x3dd53b94, v54
	v_mul_f32_e32 v55, 0x3dd53b94, v55
	v_cvt_pk_bf16_f32 v41, v54, v55
	v_mul_f32_e32 v44, 0x3dd53b94, v44
	v_mul_f32_e32 v45, 0x3dd53b94, v45
	v_cvt_pk_bf16_f32 v42, v44, v45
	v_mul_f32_e32 v46, 0x3dd53b94, v46
	v_mul_f32_e32 v47, 0x3dd53b94, v47
	v_cvt_pk_bf16_f32 v43, v46, v47
	global_store_dwordx4 v[48:49], v[40:43], off
	v_mul_f32_e32 v32, 0x3dd53b94, v32
	v_mul_f32_e32 v33, 0x3dd53b94, v33
	v_cvt_pk_bf16_f32 v32, v32, v33
	v_mul_f32_e32 v34, 0x3dd53b94, v34
	v_mul_f32_e32 v35, 0x3dd53b94, v35
	v_cvt_pk_bf16_f32 v33, v34, v35
	v_mul_f32_e32 v24, 0x3dd53b94, v24
	v_mul_f32_e32 v25, 0x3dd53b94, v25
	v_cvt_pk_bf16_f32 v34, v24, v25
	v_add_u32_e32 v24, 0xa0, v156
	v_mad_i64_i32 v[24:25], s[16:17], v24, s62, v[144:145]
	v_mul_f32_e32 v26, 0x3dd53b94, v26
	v_mul_f32_e32 v27, 0x3dd53b94, v27
	v_cvt_pk_bf16_f32 v35, v26, v27
	global_store_dwordx4 v[48:49], v[32:35], off offset:256
	s_nop 1
	v_lshl_add_u64 v[32:33], v[24:25], 0, v[146:147]
	v_mul_f32_e32 v36, 0x3dd53b94, v36
	v_mul_f32_e32 v37, 0x3dd53b94, v37
	v_cvt_pk_bf16_f32 v24, v36, v37
	v_mul_f32_e32 v38, 0x3dd53b94, v38
	v_mul_f32_e32 v39, 0x3dd53b94, v39
	v_cvt_pk_bf16_f32 v25, v38, v39
	v_mul_f32_e32 v28, 0x3dd53b94, v28
	v_mul_f32_e32 v29, 0x3dd53b94, v29
	v_cvt_pk_bf16_f32 v26, v28, v29
	v_mul_f32_e32 v30, 0x3dd53b94, v30
	v_mul_f32_e32 v31, 0x3dd53b94, v31
	v_cvt_pk_bf16_f32 v27, v30, v31
	global_store_dwordx4 v[32:33], v[24:27], off
	v_mul_f32_e32 v16, 0x3dd53b94, v16
	v_mul_f32_e32 v17, 0x3dd53b94, v17
	v_cvt_pk_bf16_f32 v16, v16, v17
	v_mul_f32_e32 v18, 0x3dd53b94, v18
	v_mul_f32_e32 v19, 0x3dd53b94, v19
	v_cvt_pk_bf16_f32 v17, v18, v19
	v_mul_f32_e32 v8, 0x3dd53b94, v8
	v_mul_f32_e32 v9, 0x3dd53b94, v9
	v_cvt_pk_bf16_f32 v18, v8, v9
	v_add_u32_e32 v8, 0xb0, v156
	v_mad_i64_i32 v[8:9], s[16:17], v8, s62, v[144:145]
	v_mul_f32_e32 v10, 0x3dd53b94, v10
	v_mul_f32_e32 v11, 0x3dd53b94, v11
	v_cvt_pk_bf16_f32 v19, v10, v11
	global_store_dwordx4 v[32:33], v[16:19], off offset:256
	s_nop 1
	v_lshl_add_u64 v[16:17], v[8:9], 0, v[146:147]
	v_mul_f32_e32 v20, 0x3dd53b94, v20
	v_mul_f32_e32 v21, 0x3dd53b94, v21
	v_cvt_pk_bf16_f32 v8, v20, v21
	v_mul_f32_e32 v22, 0x3dd53b94, v22
	v_mul_f32_e32 v23, 0x3dd53b94, v23
	v_cvt_pk_bf16_f32 v9, v22, v23
	v_mul_f32_e32 v12, 0x3dd53b94, v12
	v_mul_f32_e32 v13, 0x3dd53b94, v13
	v_cvt_pk_bf16_f32 v10, v12, v13
	v_mul_f32_e32 v14, 0x3dd53b94, v14
	v_mul_f32_e32 v15, 0x3dd53b94, v15
	v_cvt_pk_bf16_f32 v11, v14, v15
	global_store_dwordx4 v[16:17], v[8:11], off
	v_mul_f32_e32 v4, 0x3dd53b94, v4
	v_mul_f32_e32 v5, 0x3dd53b94, v5
	v_cvt_pk_bf16_f32 v4, v4, v5
	v_mul_f32_e32 v6, 0x3dd53b94, v6
	v_mul_f32_e32 v7, 0x3dd53b94, v7
	v_cvt_pk_bf16_f32 v5, v6, v7
	v_mul_f32_e32 v0, 0x3dd53b94, v0
	v_mul_f32_e32 v1, 0x3dd53b94, v1
	v_cvt_pk_bf16_f32 v6, v0, v1
	v_mul_f32_e32 v2, 0x3dd53b94, v2
	v_mul_f32_e32 v3, 0x3dd53b94, v3
	v_cvt_pk_bf16_f32 v7, v2, v3
	global_store_dwordx4 v[16:17], v[4:7], off offset:256
	s_cbranch_vccnz .LBB0_1258
	s_andn2_b64 vcc, exec, s[8:9]
	s_cbranch_vccnz .LBB0_1257
	s_barrier
	s_branch .LBB0_1257

.LBB0_1338:
	v_mov_b32_e32 v54, v191
	s_lshl_b32 s97, s4, 8
	s_add_i32 s97, s97, s79
	v_and_b32_e32 v48, 31, v54
	v_or_b32_e32 v0, s97, v48
	v_ashrrev_i32_e32 v50, 3, v54
	v_and_b32_e32 v56, 7, v54
	v_bfe_u32 v49, v54, 5, 1
	v_add_u32_e32 v0, s91, v0
	s_movk_i32 s0, 0xc00
	v_ashrrev_i32_e32 v51, 4, v54
	v_and_b32_e32 v55, 15, v54
	v_add_u32_e32 v9, s91, v50
	v_lshlrev_b32_e32 v52, 3, v56
	v_and_b32_e32 v172, 7, v51
	v_lshlrev_b32_e32 v172, 3, v172
	v_xor_b32_e32 v52, v172, v52
	v_ashrrev_i32_e32 v1, 31, v0
	v_mad_i64_i32 v[2:3], s[0:1], v0, s0, v[182:183]
	v_lshlrev_b32_e32 v180, 4, v49
	v_add_lshl_u32 v8, v51, s91, 10
	v_lshlrev_b32_e32 v53, 3, v55
	v_and_b32_e32 v172, 15, v51
	v_lshlrev_b32_e32 v172, 3, v172
	v_xor_b32_e32 v53, v172, v53
	v_lshl_or_b32 v10, v9, 6, v52
	v_add_lshl_u32 v9, v50, s92, 15
	v_lshl_add_u64 v[24:25], v[2:3], 0, v[180:181]
	v_lshlrev_b64 v[0:1], 7, v[0:1]
	v_or3_b32 v8, v8, v53, s92
	v_or3_b32 v12, v9, s91, v52
	v_add_lshl_u32 v234, v50, s92, 11
	v_add_u32_e32 v12, v12, v234
	v_mov_b32_e32 v9, v181
	global_load_dwordx4 v[96:99], v[24:25], off
	global_load_dwordx4 v[100:103], v[24:25], off offset:32
	global_load_dwordx4 v[104:107], v[24:25], off offset:64
	global_load_dwordx4 v[108:111], v[24:25], off offset:96
	global_load_dwordx4 v[112:115], v[24:25], off offset:128
	global_load_dwordx4 v[116:119], v[24:25], off offset:160
	global_load_dwordx4 v[120:123], v[24:25], off offset:192
	global_load_dwordx4 v[124:127], v[24:25], off offset:224
	v_lshl_add_u64 v[2:3], s[62:63], 0, v[0:1]
	v_lshlrev_b32_e32 v4, 5, v49
	v_mov_b32_e32 v5, v181
	v_lshl_add_u64 v[14:15], v[8:9], 1, s[64:65]
	v_add_u32_e32 v8, 0x8000, v8
	v_lshl_add_u64 v[28:29], v[2:3], 0, v[4:5]
	v_lshl_add_u64 v[0:1], s[66:67], 0, v[0:1]
	v_lshl_add_u64 v[8:9], v[8:9], 1, s[64:65]
	v_mov_b32_e32 v11, v181
	v_lshl_add_u64 v[44:45], v[0:1], 0, v[4:5]
	global_load_dwordx4 v[0:3], v[28:29], off offset:16
	global_load_dwordx4 v[4:7], v[28:29], off
	s_and_b32 s5, s97, 0xe0
	s_lshl_b32 s5, s5, 5
	s_mov_b32 m0, s5
	s_nop 0
	global_load_lds_dwordx4 v[14:15], off
	s_add_i32 m0, s5, 0x2000
	s_nop 0
	global_load_lds_dwordx4 v[8:9], off
	v_lshl_add_u64 v[8:9], v[10:11], 1, s[60:61]
	v_mov_b32_e32 v13, v181
	v_lshl_add_u64 v[10:11], v[12:13], 1, s[68:69]
	s_add_i32 m0, s5, 0x8000
	s_nop 0
	global_load_lds_dwordx4 v[8:9], off
	s_add_i32 m0, s5, 0xc000
	s_nop 0
	global_load_lds_dwordx4 v[10:11], off
	v_add_u32_e32 v8, 0x220000, v12
	v_mov_b32_e32 v9, v181
	v_lshl_add_u64 v[8:9], v[8:9], 1, s[68:69]
	s_add_i32 m0, s5, 0xe000
	s_nop 0
	global_load_lds_dwordx4 v[8:9], off
	s_nop 0
	global_load_dwordx4 v[8:11], v[44:45], off offset:16
	global_load_dwordx4 v[20:23], v[44:45], off
	global_load_dwordx4 v[12:15], v[24:25], off offset:256
	global_load_dwordx4 v[32:35], v[24:25], off offset:288
	global_load_dwordx4 v[16:19], v[24:25], off offset:320
	global_load_dwordx4 v[36:39], v[24:25], off offset:352
	s_nop 0
	global_load_dwordx4 v[24:27], v[28:29], off offset:80
	global_load_dwordx4 v[40:43], v[28:29], off offset:64
	s_nop 0
	global_load_dwordx4 v[28:31], v[44:45], off offset:80
	s_nop 0
	global_load_dwordx4 v[44:47], v[44:45], off offset:64
	v_lshlrev_b32_e32 v57, 3, v54
	v_mul_lo_u32 v58, v51, s82
	v_lshlrev_b32_e32 v54, 4, v56
	v_mul_lo_u32 v56, v50, s83
	v_lshl_add_u32 v194, v55, 4, v58
	v_and_b32_e32 v55, 0x60, v54
	v_and_b32_e32 v57, 8, v57
	v_mad_u64_u32 v[184:185], s[0:1], v50, s82, v[54:55]
	v_add_u32_e32 v54, 0, v56
	v_add3_u32 v185, v54, v57, v55
	v_add_u32_e32 v56, 0, v194
	v_add_u32_e32 v54, 0xc800, v185
	v_add_u32_e32 v58, 0, v184
	v_add_u32_e32 v55, 0xe800, v185
	s_cmp_lt_i32 s4, 0
	s_mov_b32 s52, 0
	s_waitcnt vmcnt(0)
	v_mad_u32_u24 v54, v48, s83, 0
	v_add_u32_e32 v195, v54, v180
	v_and_b32_e32 v172, 0x13, v48
	v_and_b32_e32 v175, 4, v48
	v_lshl_or_b32 v172, v175, 1, v172
	v_and_b32_e32 v175, 8, v48
	v_lshrrev_b32_e32 v175, 1, v175
	v_or_b32_e32 v172, v172, v175
	v_and_b32_e32 v175, 15, v172
	v_xor_b32_e32 v175, v175, v49
	v_lshlrev_b32_e32 v175, 4, v175
	v_lshl_or_b32 v128, v172, 8, v175
	v_xor_b32_e32 v129, 0x20, v128
	v_xor_b32_e32 v130, 0x40, v128
	v_xor_b32_e32 v131, 0x60, v128
	v_xor_b32_e32 v132, 0x80, v128
	v_xor_b32_e32 v133, 0xa0, v128
	v_xor_b32_e32 v134, 0xc0, v128
	v_xor_b32_e32 v135, 0xe0, v128
	v_bfe_u32 v175, v172, 1, 3
	v_xor_b32_e32 v175, v175, v49
	v_lshlrev_b32_e32 v175, 4, v175
	v_lshl_or_b32 v136, v172, 7, v175
	v_add_u32_e32 v136, 0x8000, v136
	v_xor_b32_e32 v137, 0x20, v136
	v_xor_b32_e32 v138, 0x40, v136
	v_xor_b32_e32 v139, 0x60, v136
	v_bfe_u32 v175, v48, 1, 3
	v_xor_b32_e32 v175, v175, v49
	v_lshlrev_b32_e32 v175, 4, v175
	v_lshl_or_b32 v140, v48, 7, v175
	v_add_u32_e32 v140, 0xc000, v140
	v_xor_b32_e32 v141, 32, v140
	v_xor_b32_e32 v144, 64, v140
	v_xor_b32_e32 v145, 64, v141
	s_waitcnt lgkmcnt(0)
	s_barrier
	s_cbranch_scc1 .LBB0_1331
	v_lshlrev_b32_e32 v55, 8, v48
	v_add3_u32 v196, v54, v55, v180
	v_and_b32_e32 v55, 0xffff0000, v36
	v_lshlrev_b32_e32 v54, 16, v36
	v_and_b32_e32 v57, 0xffff0000, v32
	v_lshlrev_b32_e32 v56, 16, v32
	v_pk_mul_f32 v[58:59], v[44:45], v[56:57]
	v_pk_mul_f32 v[44:45], v[44:45], v[54:55]
	v_pk_fma_f32 v[58:59], v[40:41], v[54:55], v[58:59]
	v_pk_fma_f32 v[40:41], v[40:41], v[56:57], v[44:45] neg_lo:[0,0,1] neg_hi:[0,0,1]
	v_lshlrev_b32_e32 v36, 16, v33
	v_cvt_pk_bf16_f32 v152, v40, v41
	v_and_b32_e32 v41, 0xffff0000, v37
	v_lshlrev_b32_e32 v40, 16, v37
	v_and_b32_e32 v37, 0xffff0000, v33
	v_pk_mul_f32 v[32:33], v[46:47], v[36:37]
	s_lshl_b32 s53, s4, 2
	v_pk_fma_f32 v[32:33], v[42:43], v[40:41], v[32:33]
	v_mov_b32_e32 v200, 0
	v_cvt_pk_bf16_f32 v149, v32, v33
	v_pk_mul_f32 v[32:33], v[46:47], v[40:41]
	s_add_i32 s53, s53, 4
	v_pk_fma_f32 v[32:33], v[42:43], v[36:37], v[32:33] neg_lo:[0,0,1] neg_hi:[0,0,1]
	v_and_b32_e32 v37, 0xffff0000, v34
	v_cvt_pk_bf16_f32 v153, v32, v33
	v_and_b32_e32 v33, 0xffff0000, v38
	v_lshlrev_b32_e32 v32, 16, v38
	v_lshlrev_b32_e32 v36, 16, v34
	v_pk_mul_f32 v[40:41], v[28:29], v[36:37]
	v_pk_mul_f32 v[28:29], v[28:29], v[32:33]
	v_pk_fma_f32 v[40:41], v[24:25], v[32:33], v[40:41]
	v_pk_fma_f32 v[24:25], v[24:25], v[36:37], v[28:29] neg_lo:[0,0,1] neg_hi:[0,0,1]
	v_and_b32_e32 v29, 0xffff0000, v35
	v_lshlrev_b32_e32 v28, 16, v35
	v_cvt_pk_bf16_f32 v154, v24, v25
	v_and_b32_e32 v25, 0xffff0000, v39
	v_lshlrev_b32_e32 v24, 16, v39
	v_pk_mul_f32 v[32:33], v[30:31], v[28:29]
	v_cvt_pk_bf16_f32 v148, v58, v59
	v_pk_fma_f32 v[32:33], v[26:27], v[24:25], v[32:33]
	v_pk_mul_f32 v[24:25], v[30:31], v[24:25]
	v_cvt_pk_bf16_f32 v150, v40, v41
	v_pk_fma_f32 v[24:25], v[26:27], v[28:29], v[24:25] neg_lo:[0,0,1] neg_hi:[0,0,1]
	v_and_b32_e32 v27, 0xffff0000, v12
	v_cvt_pk_bf16_f32 v155, v24, v25
	v_and_b32_e32 v25, 0xffff0000, v16
	v_lshlrev_b32_e32 v24, 16, v16
	v_lshlrev_b32_e32 v26, 16, v12
	v_pk_mul_f32 v[28:29], v[20:21], v[26:27]
	v_pk_mul_f32 v[20:21], v[20:21], v[24:25]
	v_pk_fma_f32 v[28:29], v[4:5], v[24:25], v[28:29]
	v_pk_fma_f32 v[4:5], v[4:5], v[26:27], v[20:21] neg_lo:[0,0,1] neg_hi:[0,0,1]
	v_lshlrev_b32_e32 v16, 16, v13
	v_cvt_pk_bf16_f32 v160, v4, v5
	v_and_b32_e32 v5, 0xffff0000, v17
	v_lshlrev_b32_e32 v4, 16, v17
	v_and_b32_e32 v17, 0xffff0000, v13
	v_pk_mul_f32 v[12:13], v[22:23], v[16:17]
	v_cvt_pk_bf16_f32 v151, v32, v33
	v_pk_fma_f32 v[12:13], v[6:7], v[4:5], v[12:13]
	v_pk_mul_f32 v[4:5], v[22:23], v[4:5]
	v_cvt_pk_bf16_f32 v157, v12, v13
	v_pk_fma_f32 v[4:5], v[6:7], v[16:17], v[4:5] neg_lo:[0,0,1] neg_hi:[0,0,1]
	v_and_b32_e32 v7, 0xffff0000, v14
	v_lshlrev_b32_e32 v6, 16, v14
	v_cvt_pk_bf16_f32 v161, v4, v5
	v_and_b32_e32 v5, 0xffff0000, v18
	v_lshlrev_b32_e32 v4, 16, v18
	v_pk_mul_f32 v[12:13], v[8:9], v[6:7]
	v_cvt_pk_bf16_f32 v156, v28, v29
	v_pk_fma_f32 v[12:13], v[0:1], v[4:5], v[12:13]
	v_pk_mul_f32 v[4:5], v[8:9], v[4:5]
	v_cvt_pk_bf16_f32 v158, v12, v13
	v_pk_fma_f32 v[0:1], v[0:1], v[6:7], v[4:5] neg_lo:[0,0,1] neg_hi:[0,0,1]
	v_and_b32_e32 v5, 0xffff0000, v15
	v_lshlrev_b32_e32 v4, 16, v15
	v_cvt_pk_bf16_f32 v162, v0, v1
	v_and_b32_e32 v1, 0xffff0000, v19
	v_lshlrev_b32_e32 v0, 16, v19
	v_pk_mul_f32 v[6:7], v[10:11], v[4:5]
	v_mov_b32_e32 v199, 0xf149f2ca
	v_pk_fma_f32 v[6:7], v[2:3], v[0:1], v[6:7]
	v_pk_mul_f32 v[0:1], v[10:11], v[0:1]
	v_cvt_pk_bf16_f32 v159, v6, v7
	v_pk_fma_f32 v[0:1], v[2:3], v[4:5], v[0:1] neg_lo:[0,0,1] neg_hi:[0,0,1]
	s_mov_b32 s33, 63
	v_cvt_pk_bf16_f32 v163, v0, v1
	v_lshlrev_b32_e32 v1, 10, v51
	v_lshlrev_b32_e32 v0, 3, v49
	v_add3_u32 v186, s93, v1, v53
	v_add_u32_e32 v1, s97, v48
	v_sub_u32_e32 v197, v1, v0
	v_lshlrev_b32_e32 v0, 6, v50
	v_add3_u32 v188, s94, v0, v52
	v_lshlrev_b32_e32 v0, 15, v50
	v_add3_u32 v198, s95, v0, v52
	v_add_lshl_u32 v234, v50, s92, 11
	v_add_u32_e32 v198, v198, v234
	v_mov_b32_e32 v64, 0
	v_mov_b32_e32 v65, 0
	v_mov_b32_e32 v66, 0
	v_mov_b32_e32 v67, 0
	v_mov_b32_e32 v68, 0
	v_mov_b32_e32 v69, 0
	v_mov_b32_e32 v70, 0
	v_mov_b32_e32 v71, 0
	s_mov_b32 s0, 0
	v_mov_b32_e32 v0, 0
	v_mov_b32_e32 v1, v200
	v_mov_b32_e32 v2, v200
	v_mov_b32_e32 v3, v200
	v_mov_b32_e32 v4, v200
	v_mov_b32_e32 v5, v200
	v_mov_b32_e32 v6, v200
	v_mov_b32_e32 v7, v200
	v_mov_b32_e32 v8, v200
	v_mov_b32_e32 v9, v200
	v_mov_b32_e32 v10, v200
	v_mov_b32_e32 v11, v200
	v_mov_b32_e32 v12, v200
	v_mov_b32_e32 v13, v200
	v_mov_b32_e32 v14, v200
	v_mov_b32_e32 v15, v200
	v_mov_b32_e32 v16, 0
	v_mov_b32_e32 v17, v200
	v_mov_b32_e32 v18, v200
	v_mov_b32_e32 v19, v200
	v_mov_b32_e32 v20, v200
	v_mov_b32_e32 v21, v200
	v_mov_b32_e32 v22, v200
	v_mov_b32_e32 v23, v200
	v_mov_b32_e32 v24, v200
	v_mov_b32_e32 v25, v200
	v_mov_b32_e32 v26, v200
	v_mov_b32_e32 v27, v200
	v_mov_b32_e32 v28, v200
	v_mov_b32_e32 v29, v200
	v_mov_b32_e32 v30, v200
	v_mov_b32_e32 v31, v200
	v_mov_b32_e32 v32, 0
	v_mov_b32_e32 v33, v200
	v_mov_b32_e32 v34, v200
	v_mov_b32_e32 v35, v200
	v_mov_b32_e32 v36, v200
	v_mov_b32_e32 v37, v200
	v_mov_b32_e32 v38, v200
	v_mov_b32_e32 v39, v200
	v_mov_b32_e32 v40, v200
	v_mov_b32_e32 v41, v200
	v_mov_b32_e32 v42, v200
	v_mov_b32_e32 v43, v200
	v_mov_b32_e32 v44, v200
	v_mov_b32_e32 v45, v200
	v_mov_b32_e32 v46, v200
	v_mov_b32_e32 v47, v200
	v_mov_b32_e32 v48, 0
	v_mov_b32_e32 v49, v200
	v_mov_b32_e32 v50, v200
	v_mov_b32_e32 v51, v200
	v_mov_b32_e32 v52, v200
	v_mov_b32_e32 v53, v200
	v_mov_b32_e32 v54, v200
	v_mov_b32_e32 v55, v200
	v_mov_b32_e32 v56, v200
	v_mov_b32_e32 v57, v200
	v_mov_b32_e32 v58, v200
	v_mov_b32_e32 v59, v200
	v_mov_b32_e32 v60, v200
	v_mov_b32_e32 v61, v200
	v_mov_b32_e32 v62, v200
	v_mov_b32_e32 v63, v200
	s_mov_b32 s55, 0
	s_mov_b32 s54, 0xff7fffff
	s_mov_b32 s26, 0xff7fffff
	v_mov_b32_e32 v230, 0
	v_mov_b32_e32 v231, v230
	v_mov_b32_e32 v232, v230
	v_mov_b32_e32 v233, v230
	v_mov_b32_e32 v234, v230
	v_mov_b32_e32 v235, v230
	v_mov_b32_e32 v236, v230
	v_mov_b32_e32 v237, v230
	v_mov_b32_e32 v238, v230
	v_mov_b32_e32 v239, v230
	v_mov_b32_e32 v240, v230
	v_mov_b32_e32 v241, v230
	v_mov_b32_e32 v242, v230
	v_mov_b32_e32 v243, v230
	v_mov_b32_e32 v244, v230
	v_mov_b32_e32 v245, v230
	s_and_b32 s52, s97, 0xe0
	s_lshl_b32 s52, s52, 5
	v_xor_b32_e32 v246, 32, v193
	v_lshlrev_b32_e32 v246, 2, v246
	v_mov_b32_e32 v64, 0xff61b1e6
	v_mov_b32_e32 v65, v64
	v_mov_b32_e32 v66, v64
	v_mov_b32_e32 v67, v64
	v_mov_b32_e32 v68, v64
	v_mov_b32_e32 v69, v64
	v_mov_b32_e32 v70, v64
	v_mov_b32_e32 v71, v64
	v_mov_b32_e32 v72, v64
	v_mov_b32_e32 v73, v64
	v_mov_b32_e32 v74, v64
	v_mov_b32_e32 v75, v64
	v_mov_b32_e32 v76, v64
	v_mov_b32_e32 v77, v64
	v_mov_b32_e32 v78, v64
	v_mov_b32_e32 v79, v64
	v_add_u32_e32 v201, 0xfffe8000, v186
	v_lshlrev_b32_e32 v201, 1, v201
	v_add_u32_e32 v187, 0x10000, v201
	v_add_u32_e32 v189, 0xfffff000, v188
	v_lshlrev_b32_e32 v189, 1, v189
	v_lshlrev_b32_e32 v194, 1, v198
	v_add_u32_e32 v195, 0x440000, v194
	s_mov_b64 s[20:21], s[64:65]
	s_mov_b64 s[22:23], s[60:61]
	s_mov_b64 s[24:25], s[68:69]
.LBB0_1340:
	s_add_u32 s20, s20, 0x20000
	s_addc_u32 s21, s21, 0
	s_add_u32 s22, s22, 0x2000
	s_addc_u32 s23, s23, 0
	s_add_u32 s24, s24, 0x80
	s_addc_u32 s25, s25, 0
	s_add_i32 m0, s52, 0x4000
	s_add_i32 s4, s97, 94
	s_nop 0
	s_nop 0
	s_nop 0
	global_load_lds_dwordx4 v201, s[20:21]
	s_add_i32 m0, s52, 0x6000
	s_nop 0
	global_load_lds_dwordx4 v187, s[20:21]
	s_add_i32 m0, s52, 0xa000
	s_nop 0
	global_load_lds_dwordx4 v189, s[22:23]
	s_add_i32 m0, s52, 0x10000
	s_nop 0
	global_load_lds_dwordx4 v194, s[24:25]
	s_add_i32 m0, s52, 0x12000
	s_nop 0
	global_load_lds_dwordx4 v195, s[24:25]
	s_cmp_gt_i32 s33, s4
	s_cbranch_scc1 .Lat_idle0
	ds_read_b128 v[202:205], v128
	ds_read_b128 v[206:209], v129
	ds_read_b128 v[210:213], v130
	ds_read_b128 v[214:217], v131
	ds_read_b128 v[218:221], v132
	ds_read_b128 v[222:225], v133
	v_exp_f32_e32 v64, v64
	v_exp_f32_e32 v65, v65
	v_add_f32_e32 v200, v200, v64
	v_exp_f32_e32 v66, v66
	s_waitcnt lgkmcnt(4)
	v_mfma_f32_32x32x16_bf16 v[80:95], v[202:205], v[96:99], v[230:245]
	ds_read_b128 v[202:205], v134
	v_add_f32_e32 v200, v200, v65
	v_exp_f32_e32 v67, v67
	v_add_f32_e32 v200, v200, v66
	v_mfma_f32_32x32x16_bf16 v[80:95], v[206:209], v[100:103], v[80:95]
	ds_read_b128 v[206:209], v135
	v_exp_f32_e32 v68, v68
	v_add_f32_e32 v200, v200, v67
	v_exp_f32_e32 v69, v69
	s_waitcnt lgkmcnt(4)
	v_mfma_f32_32x32x16_bf16 v[80:95], v[210:213], v[104:107], v[80:95]
	ds_read_b128 v[210:213], v136
	v_add_f32_e32 v200, v200, v68
	v_exp_f32_e32 v70, v70
	v_add_f32_e32 v200, v200, v69
	v_mfma_f32_32x32x16_bf16 v[80:95], v[214:217], v[108:111], v[80:95]
	ds_read_b128 v[214:217], v137
	v_exp_f32_e32 v71, v71
	v_add_f32_e32 v200, v200, v70
	v_exp_f32_e32 v72, v72
	s_waitcnt lgkmcnt(4)
	v_mfma_f32_32x32x16_bf16 v[80:95], v[218:221], v[112:115], v[80:95]
	ds_read_b128 v[218:221], v138
	v_add_f32_e32 v200, v200, v71
	v_exp_f32_e32 v73, v73
	v_add_f32_e32 v200, v200, v72
	v_mfma_f32_32x32x16_bf16 v[80:95], v[222:225], v[116:119], v[80:95]
	ds_read_b128 v[222:225], v139
	v_exp_f32_e32 v74, v74
	v_add_f32_e32 v200, v200, v73
	v_exp_f32_e32 v75, v75
	s_waitcnt lgkmcnt(4)
	v_mfma_f32_32x32x16_bf16 v[80:95], v[202:205], v[120:123], v[80:95]
	ds_read_b128 v[164:167], v144 offset:49152
	v_add_f32_e32 v200, v200, v74
	v_exp_f32_e32 v76, v76
	v_add_f32_e32 v200, v200, v75
	v_mfma_f32_32x32x16_bf16 v[80:95], v[206:209], v[124:127], v[80:95]
	ds_read_b128 v[168:171], v144 offset:53248
	v_exp_f32_e32 v77, v77
	v_add_f32_e32 v200, v200, v76
	v_exp_f32_e32 v78, v78
	s_waitcnt lgkmcnt(4)
	v_mfma_f32_32x32x16_bf16 v[80:95], v[210:213], v[160:163], v[80:95]
	ds_read_b128 v[176:179], v144 offset:57344
	v_add_f32_e32 v200, v200, v77
	v_exp_f32_e32 v79, v79
	v_add_f32_e32 v200, v200, v78
	v_mfma_f32_32x32x16_bf16 v[80:95], v[214:217], v[152:155], v[80:95]
	ds_read_b128 v[226:229], v144 offset:61440
	v_add_f32_e32 v200, v200, v79
	v_cvt_pk_bf16_f32 v64, v64, v65
	v_cvt_pk_bf16_f32 v65, v66, v67
	s_waitcnt lgkmcnt(4)
	v_mfma_f32_32x32x16_bf16 v[80:95], v[218:221], v[156:159], v[80:95]
	v_cvt_pk_bf16_f32 v66, v68, v69
	v_cvt_pk_bf16_f32 v67, v70, v71
	v_cvt_pk_bf16_f32 v68, v72, v73
	v_mfma_f32_32x32x16_bf16 v[80:95], v[222:225], v[148:151], v[80:95]
	v_cvt_pk_bf16_f32 v69, v74, v75
	v_cvt_pk_bf16_f32 v70, v76, v77
	v_cvt_pk_bf16_f32 v71, v78, v79
	s_waitcnt lgkmcnt(2)
	v_mfma_f32_32x32x16_bf16 v[48:63], v[164:167], v[64:67], v[48:63]
	ds_read_b128 v[164:167], v145 offset:49152
	v_mfma_f32_32x32x16_bf16 v[32:47], v[168:171], v[64:67], v[32:47]
	ds_read_b128 v[168:171], v145 offset:53248
	s_waitcnt lgkmcnt(2)
	v_mfma_f32_32x32x16_bf16 v[16:31], v[176:179], v[64:67], v[16:31]
	ds_read_b128 v[176:179], v145 offset:57344
	v_mfma_f32_32x32x16_bf16 v[0:15], v[226:229], v[64:67], v[0:15]
	ds_read_b128 v[226:229], v145 offset:61440
	ds_read_b128 v[202:205], v128 offset:8192
	ds_read_b128 v[206:209], v129 offset:8192
	ds_read_b128 v[210:213], v130 offset:8192
	ds_read_b128 v[214:217], v131 offset:8192
	ds_read_b128 v[218:221], v132 offset:8192
	ds_read_b128 v[222:225], v133 offset:8192
	s_cmp_gt_i32 s33, s97
	s_cbranch_scc1 .Lat_mask_a0
.Lat_mask_a0_ret:
	s_waitcnt lgkmcnt(8)
	v_mfma_f32_32x32x16_bf16 v[48:63], v[164:167], v[68:71], v[48:63]
	v_max3_f32 v172, v80, v81, v82
	v_max3_f32 v172, v172, v83, v84
	v_mfma_f32_32x32x16_bf16 v[32:47], v[168:171], v[68:71], v[32:47]
	v_max3_f32 v172, v172, v85, v86
	v_max3_f32 v172, v172, v87, v88
	s_waitcnt lgkmcnt(6)
	v_mfma_f32_32x32x16_bf16 v[16:31], v[176:179], v[68:71], v[16:31]
	v_max3_f32 v172, v172, v89, v90
	v_max3_f32 v172, v172, v91, v92
	v_mfma_f32_32x32x16_bf16 v[0:15], v[226:229], v[68:71], v[0:15]
	v_max3_f32 v172, v172, v93, v94
	v_max_f32_e32 v172, v172, v95
	v_cmp_lt_f32_e32 vcc, s54, v172
	s_cmp_lg_u64 vcc, 0
	s_cbranch_scc1 .Lat_resc_a0
.Lat_resc_a0_ret:
	v_exp_f32_e32 v80, v80
	v_exp_f32_e32 v81, v81
	v_add_f32_e32 v200, v200, v80
	v_exp_f32_e32 v82, v82
	s_waitcnt lgkmcnt(4)
	v_mfma_f32_32x32x16_bf16 v[64:79], v[202:205], v[96:99], v[230:245]
	ds_read_b128 v[202:205], v134 offset:8192
	v_add_f32_e32 v200, v200, v81
	v_exp_f32_e32 v83, v83
	v_add_f32_e32 v200, v200, v82
	v_mfma_f32_32x32x16_bf16 v[64:79], v[206:209], v[100:103], v[64:79]
	ds_read_b128 v[206:209], v135 offset:8192
	v_exp_f32_e32 v84, v84
	v_add_f32_e32 v200, v200, v83
	v_exp_f32_e32 v85, v85
	s_waitcnt lgkmcnt(4)
	v_mfma_f32_32x32x16_bf16 v[64:79], v[210:213], v[104:107], v[64:79]
	ds_read_b128 v[210:213], v136 offset:4096
	v_add_f32_e32 v200, v200, v84
	v_exp_f32_e32 v86, v86
	v_add_f32_e32 v200, v200, v85
	v_mfma_f32_32x32x16_bf16 v[64:79], v[214:217], v[108:111], v[64:79]
	ds_read_b128 v[214:217], v137 offset:4096
	v_exp_f32_e32 v87, v87
	v_add_f32_e32 v200, v200, v86
	v_exp_f32_e32 v88, v88
	s_waitcnt lgkmcnt(4)
	v_mfma_f32_32x32x16_bf16 v[64:79], v[218:221], v[112:115], v[64:79]
	ds_read_b128 v[218:221], v138 offset:4096
	v_add_f32_e32 v200, v200, v87
	v_exp_f32_e32 v89, v89
	v_add_f32_e32 v200, v200, v88
	v_mfma_f32_32x32x16_bf16 v[64:79], v[222:225], v[116:119], v[64:79]
	ds_read_b128 v[222:225], v139 offset:4096
	v_exp_f32_e32 v90, v90
	v_add_f32_e32 v200, v200, v89
	v_exp_f32_e32 v91, v91
	s_waitcnt lgkmcnt(4)
	v_mfma_f32_32x32x16_bf16 v[64:79], v[202:205], v[120:123], v[64:79]
	ds_read_b128 v[164:167], v140
	v_add_f32_e32 v200, v200, v90
	v_exp_f32_e32 v92, v92
	v_add_f32_e32 v200, v200, v91
	v_mfma_f32_32x32x16_bf16 v[64:79], v[206:209], v[124:127], v[64:79]
	ds_read_b128 v[168:171], v140 offset:4096
	v_exp_f32_e32 v93, v93
	v_add_f32_e32 v200, v200, v92
	v_exp_f32_e32 v94, v94
	s_waitcnt lgkmcnt(4)
	v_mfma_f32_32x32x16_bf16 v[64:79], v[210:213], v[160:163], v[64:79]
	ds_read_b128 v[176:179], v140 offset:8192
	v_add_f32_e32 v200, v200, v93
	v_exp_f32_e32 v95, v95
	v_add_f32_e32 v200, v200, v94
	v_mfma_f32_32x32x16_bf16 v[64:79], v[214:217], v[152:155], v[64:79]
	ds_read_b128 v[226:229], v140 offset:12288
	v_add_f32_e32 v200, v200, v95
	v_cvt_pk_bf16_f32 v80, v80, v81
	v_cvt_pk_bf16_f32 v81, v82, v83
	s_waitcnt lgkmcnt(4)
	v_mfma_f32_32x32x16_bf16 v[64:79], v[218:221], v[156:159], v[64:79]
	v_cvt_pk_bf16_f32 v82, v84, v85
	v_cvt_pk_bf16_f32 v83, v86, v87
	v_cvt_pk_bf16_f32 v84, v88, v89
	v_mfma_f32_32x32x16_bf16 v[64:79], v[222:225], v[148:151], v[64:79]
	v_cvt_pk_bf16_f32 v85, v90, v91
	v_cvt_pk_bf16_f32 v86, v92, v93
	v_cvt_pk_bf16_f32 v87, v94, v95
	s_waitcnt lgkmcnt(2)
	v_mfma_f32_32x32x16_bf16 v[48:63], v[164:167], v[80:83], v[48:63]
	ds_read_b128 v[164:167], v141
	v_mfma_f32_32x32x16_bf16 v[32:47], v[168:171], v[80:83], v[32:47]
	ds_read_b128 v[168:171], v141 offset:4096
	s_waitcnt lgkmcnt(2)
	v_mfma_f32_32x32x16_bf16 v[16:31], v[176:179], v[80:83], v[16:31]
	ds_read_b128 v[176:179], v141 offset:8192
	v_mfma_f32_32x32x16_bf16 v[0:15], v[226:229], v[80:83], v[0:15]
	ds_read_b128 v[226:229], v141 offset:12288
	s_cmp_gt_i32 s33, s97
	s_cbranch_scc1 .Lat_mask_b0
.Lat_mask_b0_ret:
	s_waitcnt lgkmcnt(2)
	v_mfma_f32_32x32x16_bf16 v[48:63], v[164:167], v[84:87], v[48:63]
	v_max3_f32 v172, v64, v65, v66
	v_max3_f32 v172, v172, v67, v68
	v_mfma_f32_32x32x16_bf16 v[32:47], v[168:171], v[84:87], v[32:47]
	v_max3_f32 v172, v172, v69, v70
	v_max3_f32 v172, v172, v71, v72
	s_waitcnt lgkmcnt(0)
	v_mfma_f32_32x32x16_bf16 v[16:31], v[176:179], v[84:87], v[16:31]
	v_max3_f32 v172, v172, v73, v74
	v_max3_f32 v172, v172, v75, v76
	v_mfma_f32_32x32x16_bf16 v[0:15], v[226:229], v[84:87], v[0:15]
	v_max3_f32 v172, v172, v77, v78
	v_max_f32_e32 v172, v172, v79
	v_cmp_lt_f32_e32 vcc, s54, v172
	s_cmp_lg_u64 vcc, 0
	s_cbranch_scc1 .Lat_resc_b0

.Lat_copy1:
	s_add_u32 s20, s20, 0x20000
	s_addc_u32 s21, s21, 0
	s_add_u32 s22, s22, 0x2000
	s_addc_u32 s23, s23, 0
	s_add_u32 s24, s24, 0x80
	s_addc_u32 s25, s25, 0
	s_add_i32 m0, s52, 0x0
	s_add_i32 s4, s97, 94
	s_nop 0
	s_nop 0
	s_nop 0
	global_load_lds_dwordx4 v201, s[20:21]
	s_add_i32 m0, s52, 0x2000
	s_nop 0
	global_load_lds_dwordx4 v187, s[20:21]
	s_add_i32 m0, s52, 0x8000
	s_nop 0
	global_load_lds_dwordx4 v189, s[22:23]
	s_add_i32 m0, s52, 0x14000
	s_nop 0
	global_load_lds_dwordx4 v194, s[24:25]
	s_add_i32 m0, s52, 0x16000
	s_nop 0
	global_load_lds_dwordx4 v195, s[24:25]
	s_cmp_gt_i32 s33, s4
	s_cbranch_scc1 .Lat_idle1
	ds_read_b128 v[202:205], v128 offset:16384
	ds_read_b128 v[206:209], v129 offset:16384
	ds_read_b128 v[210:213], v130 offset:16384
	ds_read_b128 v[214:217], v131 offset:16384
	ds_read_b128 v[218:221], v132 offset:16384
	ds_read_b128 v[222:225], v133 offset:16384
	v_exp_f32_e32 v64, v64
	v_exp_f32_e32 v65, v65
	v_add_f32_e32 v200, v200, v64
	v_exp_f32_e32 v66, v66
	s_waitcnt lgkmcnt(4)
	v_mfma_f32_32x32x16_bf16 v[80:95], v[202:205], v[96:99], v[230:245]
	ds_read_b128 v[202:205], v134 offset:16384
	v_add_f32_e32 v200, v200, v65
	v_exp_f32_e32 v67, v67
	v_add_f32_e32 v200, v200, v66
	v_mfma_f32_32x32x16_bf16 v[80:95], v[206:209], v[100:103], v[80:95]
	ds_read_b128 v[206:209], v135 offset:16384
	v_exp_f32_e32 v68, v68
	v_add_f32_e32 v200, v200, v67
	v_exp_f32_e32 v69, v69
	s_waitcnt lgkmcnt(4)
	v_mfma_f32_32x32x16_bf16 v[80:95], v[210:213], v[104:107], v[80:95]
	ds_read_b128 v[210:213], v136 offset:8192
	v_add_f32_e32 v200, v200, v68
	v_exp_f32_e32 v70, v70
	v_add_f32_e32 v200, v200, v69
	v_mfma_f32_32x32x16_bf16 v[80:95], v[214:217], v[108:111], v[80:95]
	ds_read_b128 v[214:217], v137 offset:8192
	v_exp_f32_e32 v71, v71
	v_add_f32_e32 v200, v200, v70
	v_exp_f32_e32 v72, v72
	s_waitcnt lgkmcnt(4)
	v_mfma_f32_32x32x16_bf16 v[80:95], v[218:221], v[112:115], v[80:95]
	ds_read_b128 v[218:221], v138 offset:8192
	v_add_f32_e32 v200, v200, v71
	v_exp_f32_e32 v73, v73
	v_add_f32_e32 v200, v200, v72
	v_mfma_f32_32x32x16_bf16 v[80:95], v[222:225], v[116:119], v[80:95]
	ds_read_b128 v[222:225], v139 offset:8192
	v_exp_f32_e32 v74, v74
	v_add_f32_e32 v200, v200, v73
	v_exp_f32_e32 v75, v75
	s_waitcnt lgkmcnt(4)
	v_mfma_f32_32x32x16_bf16 v[80:95], v[202:205], v[120:123], v[80:95]
	ds_read_b128 v[164:167], v144
	v_add_f32_e32 v200, v200, v74
	v_exp_f32_e32 v76, v76
	v_add_f32_e32 v200, v200, v75
	v_mfma_f32_32x32x16_bf16 v[80:95], v[206:209], v[124:127], v[80:95]
	ds_read_b128 v[168:171], v144 offset:4096
	v_exp_f32_e32 v77, v77
	v_add_f32_e32 v200, v200, v76
	v_exp_f32_e32 v78, v78
	s_waitcnt lgkmcnt(4)
	v_mfma_f32_32x32x16_bf16 v[80:95], v[210:213], v[160:163], v[80:95]
	ds_read_b128 v[176:179], v144 offset:8192
	v_add_f32_e32 v200, v200, v77
	v_exp_f32_e32 v79, v79
	v_add_f32_e32 v200, v200, v78
	v_mfma_f32_32x32x16_bf16 v[80:95], v[214:217], v[152:155], v[80:95]
	ds_read_b128 v[226:229], v144 offset:12288
	v_add_f32_e32 v200, v200, v79
	v_cvt_pk_bf16_f32 v64, v64, v65
	v_cvt_pk_bf16_f32 v65, v66, v67
	s_waitcnt lgkmcnt(4)
	v_mfma_f32_32x32x16_bf16 v[80:95], v[218:221], v[156:159], v[80:95]
	v_cvt_pk_bf16_f32 v66, v68, v69
	v_cvt_pk_bf16_f32 v67, v70, v71
	v_cvt_pk_bf16_f32 v68, v72, v73
	v_mfma_f32_32x32x16_bf16 v[80:95], v[222:225], v[148:151], v[80:95]
	v_cvt_pk_bf16_f32 v69, v74, v75
	v_cvt_pk_bf16_f32 v70, v76, v77
	v_cvt_pk_bf16_f32 v71, v78, v79
	s_waitcnt lgkmcnt(2)
	v_mfma_f32_32x32x16_bf16 v[48:63], v[164:167], v[64:67], v[48:63]
	ds_read_b128 v[164:167], v145
	v_mfma_f32_32x32x16_bf16 v[32:47], v[168:171], v[64:67], v[32:47]
	ds_read_b128 v[168:171], v145 offset:4096
	s_waitcnt lgkmcnt(2)
	v_mfma_f32_32x32x16_bf16 v[16:31], v[176:179], v[64:67], v[16:31]
	ds_read_b128 v[176:179], v145 offset:8192
	v_mfma_f32_32x32x16_bf16 v[0:15], v[226:229], v[64:67], v[0:15]
	ds_read_b128 v[226:229], v145 offset:12288
	ds_read_b128 v[202:205], v128 offset:24576
	ds_read_b128 v[206:209], v129 offset:24576
	ds_read_b128 v[210:213], v130 offset:24576
	ds_read_b128 v[214:217], v131 offset:24576
	ds_read_b128 v[218:221], v132 offset:24576
	ds_read_b128 v[222:225], v133 offset:24576
	s_cmp_gt_i32 s33, s97
	s_cbranch_scc1 .Lat_mask_a1

.Lat_resc_a1_ret:
	v_exp_f32_e32 v80, v80
	v_exp_f32_e32 v81, v81
	v_add_f32_e32 v200, v200, v80
	v_exp_f32_e32 v82, v82
	s_waitcnt lgkmcnt(4)
	v_mfma_f32_32x32x16_bf16 v[64:79], v[202:205], v[96:99], v[230:245]
	ds_read_b128 v[202:205], v134 offset:24576
	v_add_f32_e32 v200, v200, v81
	v_exp_f32_e32 v83, v83
	v_add_f32_e32 v200, v200, v82
	v_mfma_f32_32x32x16_bf16 v[64:79], v[206:209], v[100:103], v[64:79]
	ds_read_b128 v[206:209], v135 offset:24576
	v_exp_f32_e32 v84, v84
	v_add_f32_e32 v200, v200, v83
	v_exp_f32_e32 v85, v85
	s_waitcnt lgkmcnt(4)
	v_mfma_f32_32x32x16_bf16 v[64:79], v[210:213], v[104:107], v[64:79]
	ds_read_b128 v[210:213], v136 offset:12288
	v_add_f32_e32 v200, v200, v84
	v_exp_f32_e32 v86, v86
	v_add_f32_e32 v200, v200, v85
	v_mfma_f32_32x32x16_bf16 v[64:79], v[214:217], v[108:111], v[64:79]
	ds_read_b128 v[214:217], v137 offset:12288
	v_exp_f32_e32 v87, v87
	v_add_f32_e32 v200, v200, v86
	v_exp_f32_e32 v88, v88
	s_waitcnt lgkmcnt(4)
	v_mfma_f32_32x32x16_bf16 v[64:79], v[218:221], v[112:115], v[64:79]
	ds_read_b128 v[218:221], v138 offset:12288
	v_add_f32_e32 v200, v200, v87
	v_exp_f32_e32 v89, v89
	v_add_f32_e32 v200, v200, v88
	v_mfma_f32_32x32x16_bf16 v[64:79], v[222:225], v[116:119], v[64:79]
	ds_read_b128 v[222:225], v139 offset:12288
	v_exp_f32_e32 v90, v90
	v_add_f32_e32 v200, v200, v89
	v_exp_f32_e32 v91, v91
	s_waitcnt lgkmcnt(4)
	v_mfma_f32_32x32x16_bf16 v[64:79], v[202:205], v[120:123], v[64:79]
	ds_read_b128 v[164:167], v140 offset:16384
	v_add_f32_e32 v200, v200, v90
	v_exp_f32_e32 v92, v92
	v_add_f32_e32 v200, v200, v91
	v_mfma_f32_32x32x16_bf16 v[64:79], v[206:209], v[124:127], v[64:79]
	ds_read_b128 v[168:171], v140 offset:20480
	v_exp_f32_e32 v93, v93
	v_add_f32_e32 v200, v200, v92
	v_exp_f32_e32 v94, v94
	s_waitcnt lgkmcnt(4)
	v_mfma_f32_32x32x16_bf16 v[64:79], v[210:213], v[160:163], v[64:79]
	ds_read_b128 v[176:179], v140 offset:24576
	v_add_f32_e32 v200, v200, v93
	v_exp_f32_e32 v95, v95
	v_add_f32_e32 v200, v200, v94
	v_mfma_f32_32x32x16_bf16 v[64:79], v[214:217], v[152:155], v[64:79]
	ds_read_b128 v[226:229], v140 offset:28672
	v_add_f32_e32 v200, v200, v95
	v_cvt_pk_bf16_f32 v80, v80, v81
	v_cvt_pk_bf16_f32 v81, v82, v83
	s_waitcnt lgkmcnt(4)
	v_mfma_f32_32x32x16_bf16 v[64:79], v[218:221], v[156:159], v[64:79]
	v_cvt_pk_bf16_f32 v82, v84, v85
	v_cvt_pk_bf16_f32 v83, v86, v87
	v_cvt_pk_bf16_f32 v84, v88, v89
	v_mfma_f32_32x32x16_bf16 v[64:79], v[222:225], v[148:151], v[64:79]
	v_cvt_pk_bf16_f32 v85, v90, v91
	v_cvt_pk_bf16_f32 v86, v92, v93
	v_cvt_pk_bf16_f32 v87, v94, v95
	s_waitcnt lgkmcnt(2)
	v_mfma_f32_32x32x16_bf16 v[48:63], v[164:167], v[80:83], v[48:63]
	ds_read_b128 v[164:167], v141 offset:16384
	v_mfma_f32_32x32x16_bf16 v[32:47], v[168:171], v[80:83], v[32:47]
	ds_read_b128 v[168:171], v141 offset:20480
	s_waitcnt lgkmcnt(2)
	v_mfma_f32_32x32x16_bf16 v[16:31], v[176:179], v[80:83], v[16:31]
	ds_read_b128 v[176:179], v141 offset:24576
	v_mfma_f32_32x32x16_bf16 v[0:15], v[226:229], v[80:83], v[0:15]
	ds_read_b128 v[226:229], v141 offset:28672
	s_cmp_gt_i32 s33, s97
	s_cbranch_scc1 .Lat_mask_b1

.Lat_copy2:
	s_add_u32 s20, s20, 0x20000
	s_addc_u32 s21, s21, 0
	s_add_u32 s22, s22, 0x2000
	s_addc_u32 s23, s23, 0
	s_add_u32 s24, s24, 0x80
	s_addc_u32 s25, s25, 0
	s_add_i32 m0, s52, 0x4000
	s_add_i32 s4, s97, 94
	s_nop 0
	s_nop 0
	s_nop 0
	global_load_lds_dwordx4 v201, s[20:21]
	s_add_i32 m0, s52, 0x6000
	s_nop 0
	global_load_lds_dwordx4 v187, s[20:21]
	s_add_i32 m0, s52, 0xa000
	s_nop 0
	global_load_lds_dwordx4 v189, s[22:23]
	s_add_i32 m0, s52, 0x18000
	s_nop 0
	global_load_lds_dwordx4 v194, s[24:25]
	s_add_i32 m0, s52, 0x1a000
	s_nop 0
	global_load_lds_dwordx4 v195, s[24:25]
	s_cmp_gt_i32 s33, s4
	s_cbranch_scc1 .Lat_idle2
	ds_read_b128 v[202:205], v128
	ds_read_b128 v[206:209], v129
	ds_read_b128 v[210:213], v130
	ds_read_b128 v[214:217], v131
	ds_read_b128 v[218:221], v132
	ds_read_b128 v[222:225], v133
	v_exp_f32_e32 v64, v64
	v_exp_f32_e32 v65, v65
	v_add_f32_e32 v200, v200, v64
	v_exp_f32_e32 v66, v66
	s_waitcnt lgkmcnt(4)
	v_mfma_f32_32x32x16_bf16 v[80:95], v[202:205], v[96:99], v[230:245]
	ds_read_b128 v[202:205], v134
	v_add_f32_e32 v200, v200, v65
	v_exp_f32_e32 v67, v67
	v_add_f32_e32 v200, v200, v66
	v_mfma_f32_32x32x16_bf16 v[80:95], v[206:209], v[100:103], v[80:95]
	ds_read_b128 v[206:209], v135
	v_exp_f32_e32 v68, v68
	v_add_f32_e32 v200, v200, v67
	v_exp_f32_e32 v69, v69
	s_waitcnt lgkmcnt(4)
	v_mfma_f32_32x32x16_bf16 v[80:95], v[210:213], v[104:107], v[80:95]
	ds_read_b128 v[210:213], v136
	v_add_f32_e32 v200, v200, v68
	v_exp_f32_e32 v70, v70
	v_add_f32_e32 v200, v200, v69
	v_mfma_f32_32x32x16_bf16 v[80:95], v[214:217], v[108:111], v[80:95]
	ds_read_b128 v[214:217], v137
	v_exp_f32_e32 v71, v71
	v_add_f32_e32 v200, v200, v70
	v_exp_f32_e32 v72, v72
	s_waitcnt lgkmcnt(4)
	v_mfma_f32_32x32x16_bf16 v[80:95], v[218:221], v[112:115], v[80:95]
	ds_read_b128 v[218:221], v138
	v_add_f32_e32 v200, v200, v71
	v_exp_f32_e32 v73, v73
	v_add_f32_e32 v200, v200, v72
	v_mfma_f32_32x32x16_bf16 v[80:95], v[222:225], v[116:119], v[80:95]
	ds_read_b128 v[222:225], v139
	v_exp_f32_e32 v74, v74
	v_add_f32_e32 v200, v200, v73
	v_exp_f32_e32 v75, v75
	s_waitcnt lgkmcnt(4)
	v_mfma_f32_32x32x16_bf16 v[80:95], v[202:205], v[120:123], v[80:95]
	ds_read_b128 v[164:167], v144 offset:16384
	v_add_f32_e32 v200, v200, v74
	v_exp_f32_e32 v76, v76
	v_add_f32_e32 v200, v200, v75
	v_mfma_f32_32x32x16_bf16 v[80:95], v[206:209], v[124:127], v[80:95]
	ds_read_b128 v[168:171], v144 offset:20480
	v_exp_f32_e32 v77, v77
	v_add_f32_e32 v200, v200, v76
	v_exp_f32_e32 v78, v78
	s_waitcnt lgkmcnt(4)
	v_mfma_f32_32x32x16_bf16 v[80:95], v[210:213], v[160:163], v[80:95]
	ds_read_b128 v[176:179], v144 offset:24576
	v_add_f32_e32 v200, v200, v77
	v_exp_f32_e32 v79, v79
	v_add_f32_e32 v200, v200, v78
	v_mfma_f32_32x32x16_bf16 v[80:95], v[214:217], v[152:155], v[80:95]
	ds_read_b128 v[226:229], v144 offset:28672
	v_add_f32_e32 v200, v200, v79
	v_cvt_pk_bf16_f32 v64, v64, v65
	v_cvt_pk_bf16_f32 v65, v66, v67
	s_waitcnt lgkmcnt(4)
	v_mfma_f32_32x32x16_bf16 v[80:95], v[218:221], v[156:159], v[80:95]
	v_cvt_pk_bf16_f32 v66, v68, v69
	v_cvt_pk_bf16_f32 v67, v70, v71
	v_cvt_pk_bf16_f32 v68, v72, v73
	v_mfma_f32_32x32x16_bf16 v[80:95], v[222:225], v[148:151], v[80:95]
	v_cvt_pk_bf16_f32 v69, v74, v75
	v_cvt_pk_bf16_f32 v70, v76, v77
	v_cvt_pk_bf16_f32 v71, v78, v79
	s_waitcnt lgkmcnt(2)
	v_mfma_f32_32x32x16_bf16 v[48:63], v[164:167], v[64:67], v[48:63]
	ds_read_b128 v[164:167], v145 offset:16384
	v_mfma_f32_32x32x16_bf16 v[32:47], v[168:171], v[64:67], v[32:47]
	ds_read_b128 v[168:171], v145 offset:20480
	s_waitcnt lgkmcnt(2)
	v_mfma_f32_32x32x16_bf16 v[16:31], v[176:179], v[64:67], v[16:31]
	ds_read_b128 v[176:179], v145 offset:24576
	v_mfma_f32_32x32x16_bf16 v[0:15], v[226:229], v[64:67], v[0:15]
	ds_read_b128 v[226:229], v145 offset:28672
	ds_read_b128 v[202:205], v128 offset:8192
	ds_read_b128 v[206:209], v129 offset:8192
	ds_read_b128 v[210:213], v130 offset:8192
	ds_read_b128 v[214:217], v131 offset:8192
	ds_read_b128 v[218:221], v132 offset:8192
	ds_read_b128 v[222:225], v133 offset:8192
	s_cmp_gt_i32 s33, s97
	s_cbranch_scc1 .Lat_mask_a2

.Lat_resc_a2_ret:
	v_exp_f32_e32 v80, v80
	v_exp_f32_e32 v81, v81
	v_add_f32_e32 v200, v200, v80
	v_exp_f32_e32 v82, v82
	s_waitcnt lgkmcnt(4)
	v_mfma_f32_32x32x16_bf16 v[64:79], v[202:205], v[96:99], v[230:245]
	ds_read_b128 v[202:205], v134 offset:8192
	v_add_f32_e32 v200, v200, v81
	v_exp_f32_e32 v83, v83
	v_add_f32_e32 v200, v200, v82
	v_mfma_f32_32x32x16_bf16 v[64:79], v[206:209], v[100:103], v[64:79]
	ds_read_b128 v[206:209], v135 offset:8192
	v_exp_f32_e32 v84, v84
	v_add_f32_e32 v200, v200, v83
	v_exp_f32_e32 v85, v85
	s_waitcnt lgkmcnt(4)
	v_mfma_f32_32x32x16_bf16 v[64:79], v[210:213], v[104:107], v[64:79]
	ds_read_b128 v[210:213], v136 offset:4096
	v_add_f32_e32 v200, v200, v84
	v_exp_f32_e32 v86, v86
	v_add_f32_e32 v200, v200, v85
	v_mfma_f32_32x32x16_bf16 v[64:79], v[214:217], v[108:111], v[64:79]
	ds_read_b128 v[214:217], v137 offset:4096
	v_exp_f32_e32 v87, v87
	v_add_f32_e32 v200, v200, v86
	v_exp_f32_e32 v88, v88
	s_waitcnt lgkmcnt(4)
	v_mfma_f32_32x32x16_bf16 v[64:79], v[218:221], v[112:115], v[64:79]
	ds_read_b128 v[218:221], v138 offset:4096
	v_add_f32_e32 v200, v200, v87
	v_exp_f32_e32 v89, v89
	v_add_f32_e32 v200, v200, v88
	v_mfma_f32_32x32x16_bf16 v[64:79], v[222:225], v[116:119], v[64:79]
	ds_read_b128 v[222:225], v139 offset:4096
	v_exp_f32_e32 v90, v90
	v_add_f32_e32 v200, v200, v89
	v_exp_f32_e32 v91, v91
	s_waitcnt lgkmcnt(4)
	v_mfma_f32_32x32x16_bf16 v[64:79], v[202:205], v[120:123], v[64:79]
	ds_read_b128 v[164:167], v140 offset:32768
	v_add_f32_e32 v200, v200, v90
	v_exp_f32_e32 v92, v92
	v_add_f32_e32 v200, v200, v91
	v_mfma_f32_32x32x16_bf16 v[64:79], v[206:209], v[124:127], v[64:79]
	ds_read_b128 v[168:171], v140 offset:36864
	v_exp_f32_e32 v93, v93
	v_add_f32_e32 v200, v200, v92
	v_exp_f32_e32 v94, v94
	s_waitcnt lgkmcnt(4)
	v_mfma_f32_32x32x16_bf16 v[64:79], v[210:213], v[160:163], v[64:79]
	ds_read_b128 v[176:179], v140 offset:40960
	v_add_f32_e32 v200, v200, v93
	v_exp_f32_e32 v95, v95
	v_add_f32_e32 v200, v200, v94
	v_mfma_f32_32x32x16_bf16 v[64:79], v[214:217], v[152:155], v[64:79]
	ds_read_b128 v[226:229], v140 offset:45056
	v_add_f32_e32 v200, v200, v95
	v_cvt_pk_bf16_f32 v80, v80, v81
	v_cvt_pk_bf16_f32 v81, v82, v83
	s_waitcnt lgkmcnt(4)
	v_mfma_f32_32x32x16_bf16 v[64:79], v[218:221], v[156:159], v[64:79]
	v_cvt_pk_bf16_f32 v82, v84, v85
	v_cvt_pk_bf16_f32 v83, v86, v87
	v_cvt_pk_bf16_f32 v84, v88, v89
	v_mfma_f32_32x32x16_bf16 v[64:79], v[222:225], v[148:151], v[64:79]
	v_cvt_pk_bf16_f32 v85, v90, v91
	v_cvt_pk_bf16_f32 v86, v92, v93
	v_cvt_pk_bf16_f32 v87, v94, v95
	s_waitcnt lgkmcnt(2)
	v_mfma_f32_32x32x16_bf16 v[48:63], v[164:167], v[80:83], v[48:63]
	ds_read_b128 v[164:167], v141 offset:32768
	v_mfma_f32_32x32x16_bf16 v[32:47], v[168:171], v[80:83], v[32:47]
	ds_read_b128 v[168:171], v141 offset:36864
	s_waitcnt lgkmcnt(2)
	v_mfma_f32_32x32x16_bf16 v[16:31], v[176:179], v[80:83], v[16:31]
	ds_read_b128 v[176:179], v141 offset:40960
	v_mfma_f32_32x32x16_bf16 v[0:15], v[226:229], v[80:83], v[0:15]
	ds_read_b128 v[226:229], v141 offset:45056
	s_cmp_gt_i32 s33, s97
	s_cbranch_scc1 .Lat_mask_b2

.Lat_copy3:
	s_add_i32 s4, s0, 1
	s_cmp_lt_i32 s4, s53
	s_cbranch_scc0 .Lat_skip_ld
	s_add_u32 s20, s20, 0x20000
	s_addc_u32 s21, s21, 0
	s_add_u32 s22, s22, 0x2000
	s_addc_u32 s23, s23, 0
	s_add_u32 s24, s24, 0x80
	s_addc_u32 s25, s25, 0
	s_add_i32 m0, s52, 0x0
	s_add_i32 s4, s97, 94
	s_nop 0
	s_nop 0
	s_nop 0
	global_load_lds_dwordx4 v201, s[20:21]
	s_add_i32 m0, s52, 0x2000
	s_nop 0
	global_load_lds_dwordx4 v187, s[20:21]
	s_add_i32 m0, s52, 0x8000
	s_nop 0
	global_load_lds_dwordx4 v189, s[22:23]
	s_add_i32 m0, s52, 0xc000
	s_nop 0
	global_load_lds_dwordx4 v194, s[24:25]
	s_add_i32 m0, s52, 0xe000
	s_nop 0
	global_load_lds_dwordx4 v195, s[24:25]
.Lat_skip_ld:
	s_add_i32 s4, s97, 94
	s_cmp_gt_i32 s33, s4
	s_cbranch_scc1 .Lat_idle3
	ds_read_b128 v[202:205], v128 offset:16384
	ds_read_b128 v[206:209], v129 offset:16384
	ds_read_b128 v[210:213], v130 offset:16384
	ds_read_b128 v[214:217], v131 offset:16384
	ds_read_b128 v[218:221], v132 offset:16384
	ds_read_b128 v[222:225], v133 offset:16384
	v_exp_f32_e32 v64, v64
	v_exp_f32_e32 v65, v65
	v_add_f32_e32 v200, v200, v64
	v_exp_f32_e32 v66, v66
	s_waitcnt lgkmcnt(4)
	v_mfma_f32_32x32x16_bf16 v[80:95], v[202:205], v[96:99], v[230:245]
	ds_read_b128 v[202:205], v134 offset:16384
	v_add_f32_e32 v200, v200, v65
	v_exp_f32_e32 v67, v67
	v_add_f32_e32 v200, v200, v66
	v_mfma_f32_32x32x16_bf16 v[80:95], v[206:209], v[100:103], v[80:95]
	ds_read_b128 v[206:209], v135 offset:16384
	v_exp_f32_e32 v68, v68
	v_add_f32_e32 v200, v200, v67
	v_exp_f32_e32 v69, v69
	s_waitcnt lgkmcnt(4)
	v_mfma_f32_32x32x16_bf16 v[80:95], v[210:213], v[104:107], v[80:95]
	ds_read_b128 v[210:213], v136 offset:8192
	v_add_f32_e32 v200, v200, v68
	v_exp_f32_e32 v70, v70
	v_add_f32_e32 v200, v200, v69
	v_mfma_f32_32x32x16_bf16 v[80:95], v[214:217], v[108:111], v[80:95]
	ds_read_b128 v[214:217], v137 offset:8192
	v_exp_f32_e32 v71, v71
	v_add_f32_e32 v200, v200, v70
	v_exp_f32_e32 v72, v72
	s_waitcnt lgkmcnt(4)
	v_mfma_f32_32x32x16_bf16 v[80:95], v[218:221], v[112:115], v[80:95]
	ds_read_b128 v[218:221], v138 offset:8192
	v_add_f32_e32 v200, v200, v71
	v_exp_f32_e32 v73, v73
	v_add_f32_e32 v200, v200, v72
	v_mfma_f32_32x32x16_bf16 v[80:95], v[222:225], v[116:119], v[80:95]
	ds_read_b128 v[222:225], v139 offset:8192
	v_exp_f32_e32 v74, v74
	v_add_f32_e32 v200, v200, v73
	v_exp_f32_e32 v75, v75
	s_waitcnt lgkmcnt(4)
	v_mfma_f32_32x32x16_bf16 v[80:95], v[202:205], v[120:123], v[80:95]
	ds_read_b128 v[164:167], v144 offset:32768
	v_add_f32_e32 v200, v200, v74
	v_exp_f32_e32 v76, v76
	v_add_f32_e32 v200, v200, v75
	v_mfma_f32_32x32x16_bf16 v[80:95], v[206:209], v[124:127], v[80:95]
	ds_read_b128 v[168:171], v144 offset:36864
	v_exp_f32_e32 v77, v77
	v_add_f32_e32 v200, v200, v76
	v_exp_f32_e32 v78, v78
	s_waitcnt lgkmcnt(4)
	v_mfma_f32_32x32x16_bf16 v[80:95], v[210:213], v[160:163], v[80:95]
	ds_read_b128 v[176:179], v144 offset:40960
	v_add_f32_e32 v200, v200, v77
	v_exp_f32_e32 v79, v79
	v_add_f32_e32 v200, v200, v78
	v_mfma_f32_32x32x16_bf16 v[80:95], v[214:217], v[152:155], v[80:95]
	ds_read_b128 v[226:229], v144 offset:45056
	v_add_f32_e32 v200, v200, v79
	v_cvt_pk_bf16_f32 v64, v64, v65
	v_cvt_pk_bf16_f32 v65, v66, v67
	s_waitcnt lgkmcnt(4)
	v_mfma_f32_32x32x16_bf16 v[80:95], v[218:221], v[156:159], v[80:95]
	v_cvt_pk_bf16_f32 v66, v68, v69
	v_cvt_pk_bf16_f32 v67, v70, v71
	v_cvt_pk_bf16_f32 v68, v72, v73
	v_mfma_f32_32x32x16_bf16 v[80:95], v[222:225], v[148:151], v[80:95]
	v_cvt_pk_bf16_f32 v69, v74, v75
	v_cvt_pk_bf16_f32 v70, v76, v77
	v_cvt_pk_bf16_f32 v71, v78, v79
	s_waitcnt lgkmcnt(2)
	v_mfma_f32_32x32x16_bf16 v[48:63], v[164:167], v[64:67], v[48:63]
	ds_read_b128 v[164:167], v145 offset:32768
	v_mfma_f32_32x32x16_bf16 v[32:47], v[168:171], v[64:67], v[32:47]
	ds_read_b128 v[168:171], v145 offset:36864
	s_waitcnt lgkmcnt(2)
	v_mfma_f32_32x32x16_bf16 v[16:31], v[176:179], v[64:67], v[16:31]
	ds_read_b128 v[176:179], v145 offset:40960
	v_mfma_f32_32x32x16_bf16 v[0:15], v[226:229], v[64:67], v[0:15]
	ds_read_b128 v[226:229], v145 offset:45056
	ds_read_b128 v[202:205], v128 offset:24576
	ds_read_b128 v[206:209], v129 offset:24576
	ds_read_b128 v[210:213], v130 offset:24576
	ds_read_b128 v[214:217], v131 offset:24576
	ds_read_b128 v[218:221], v132 offset:24576
	ds_read_b128 v[222:225], v133 offset:24576
	s_cmp_gt_i32 s33, s97
	s_cbranch_scc1 .Lat_mask_a3

.Lat_resc_a3_ret:
	v_exp_f32_e32 v80, v80
	v_exp_f32_e32 v81, v81
	v_add_f32_e32 v200, v200, v80
	v_exp_f32_e32 v82, v82
	s_waitcnt lgkmcnt(4)
	v_mfma_f32_32x32x16_bf16 v[64:79], v[202:205], v[96:99], v[230:245]
	ds_read_b128 v[202:205], v134 offset:24576
	v_add_f32_e32 v200, v200, v81
	v_exp_f32_e32 v83, v83
	v_add_f32_e32 v200, v200, v82
	v_mfma_f32_32x32x16_bf16 v[64:79], v[206:209], v[100:103], v[64:79]
	ds_read_b128 v[206:209], v135 offset:24576
	v_exp_f32_e32 v84, v84
	v_add_f32_e32 v200, v200, v83
	v_exp_f32_e32 v85, v85
	s_waitcnt lgkmcnt(4)
	v_mfma_f32_32x32x16_bf16 v[64:79], v[210:213], v[104:107], v[64:79]
	ds_read_b128 v[210:213], v136 offset:12288
	v_add_f32_e32 v200, v200, v84
	v_exp_f32_e32 v86, v86
	v_add_f32_e32 v200, v200, v85
	v_mfma_f32_32x32x16_bf16 v[64:79], v[214:217], v[108:111], v[64:79]
	ds_read_b128 v[214:217], v137 offset:12288
	v_exp_f32_e32 v87, v87
	v_add_f32_e32 v200, v200, v86
	v_exp_f32_e32 v88, v88
	s_waitcnt lgkmcnt(4)
	v_mfma_f32_32x32x16_bf16 v[64:79], v[218:221], v[112:115], v[64:79]
	ds_read_b128 v[218:221], v138 offset:12288
	v_add_f32_e32 v200, v200, v87
	v_exp_f32_e32 v89, v89
	v_add_f32_e32 v200, v200, v88
	v_mfma_f32_32x32x16_bf16 v[64:79], v[222:225], v[116:119], v[64:79]
	ds_read_b128 v[222:225], v139 offset:12288
	v_exp_f32_e32 v90, v90
	v_add_f32_e32 v200, v200, v89
	v_exp_f32_e32 v91, v91
	s_waitcnt lgkmcnt(4)
	v_mfma_f32_32x32x16_bf16 v[64:79], v[202:205], v[120:123], v[64:79]
	ds_read_b128 v[164:167], v140 offset:49152
	v_add_f32_e32 v200, v200, v90
	v_exp_f32_e32 v92, v92
	v_add_f32_e32 v200, v200, v91
	v_mfma_f32_32x32x16_bf16 v[64:79], v[206:209], v[124:127], v[64:79]
	ds_read_b128 v[168:171], v140 offset:53248
	v_exp_f32_e32 v93, v93
	v_add_f32_e32 v200, v200, v92
	v_exp_f32_e32 v94, v94
	s_waitcnt lgkmcnt(4)
	v_mfma_f32_32x32x16_bf16 v[64:79], v[210:213], v[160:163], v[64:79]
	ds_read_b128 v[176:179], v140 offset:57344
	v_add_f32_e32 v200, v200, v93
	v_exp_f32_e32 v95, v95
	v_add_f32_e32 v200, v200, v94
	v_mfma_f32_32x32x16_bf16 v[64:79], v[214:217], v[152:155], v[64:79]
	ds_read_b128 v[226:229], v140 offset:61440
	v_add_f32_e32 v200, v200, v95
	v_cvt_pk_bf16_f32 v80, v80, v81
	v_cvt_pk_bf16_f32 v81, v82, v83
	s_waitcnt lgkmcnt(4)
	v_mfma_f32_32x32x16_bf16 v[64:79], v[218:221], v[156:159], v[64:79]
	v_cvt_pk_bf16_f32 v82, v84, v85
	v_cvt_pk_bf16_f32 v83, v86, v87
	v_cvt_pk_bf16_f32 v84, v88, v89
	v_mfma_f32_32x32x16_bf16 v[64:79], v[222:225], v[148:151], v[64:79]
	v_cvt_pk_bf16_f32 v85, v90, v91
	v_cvt_pk_bf16_f32 v86, v92, v93
	v_cvt_pk_bf16_f32 v87, v94, v95
	s_waitcnt lgkmcnt(2)
	v_mfma_f32_32x32x16_bf16 v[48:63], v[164:167], v[80:83], v[48:63]
	ds_read_b128 v[164:167], v141 offset:49152
	v_mfma_f32_32x32x16_bf16 v[32:47], v[168:171], v[80:83], v[32:47]
	ds_read_b128 v[168:171], v141 offset:53248
	s_waitcnt lgkmcnt(2)
	v_mfma_f32_32x32x16_bf16 v[16:31], v[176:179], v[80:83], v[16:31]
	ds_read_b128 v[176:179], v141 offset:57344
	v_mfma_f32_32x32x16_bf16 v[0:15], v[226:229], v[80:83], v[0:15]
	ds_read_b128 v[226:229], v141 offset:61440
	s_cmp_gt_i32 s33, s97
	s_cbranch_scc1 .Lat_mask_b3

.Lat_resc_b3_ret:
	s_add_i32 s33, s33, 64
	v_subrev_u32_e32 v197, 64, v197
	s_add_i32 s0, s0, 1
	s_cmp_eq_u32 s53, s0
	s_waitcnt vmcnt(0) lgkmcnt(0)
	s_barrier
	s_cbranch_scc0 .LBB0_1340
	v_exp_f32_e32 v64, v64
	v_exp_f32_e32 v65, v65
	v_add_f32_e32 v200, v200, v64
	v_exp_f32_e32 v66, v66
	v_add_f32_e32 v200, v200, v65
	v_exp_f32_e32 v67, v67
	v_add_f32_e32 v200, v200, v66
	v_exp_f32_e32 v68, v68
	v_add_f32_e32 v200, v200, v67
	v_exp_f32_e32 v69, v69
	v_add_f32_e32 v200, v200, v68
	v_exp_f32_e32 v70, v70
	v_add_f32_e32 v200, v200, v69
	v_exp_f32_e32 v71, v71
	v_add_f32_e32 v200, v200, v70
	v_exp_f32_e32 v72, v72
	v_add_f32_e32 v200, v200, v71
	v_exp_f32_e32 v73, v73
	v_add_f32_e32 v200, v200, v72
	v_exp_f32_e32 v74, v74
	v_add_f32_e32 v200, v200, v73
	v_exp_f32_e32 v75, v75
	v_add_f32_e32 v200, v200, v74
	v_exp_f32_e32 v76, v76
	v_add_f32_e32 v200, v200, v75
	v_exp_f32_e32 v77, v77
	v_add_f32_e32 v200, v200, v76
	v_exp_f32_e32 v78, v78
	v_add_f32_e32 v200, v200, v77
	v_exp_f32_e32 v79, v79
	v_add_f32_e32 v200, v200, v78
	v_add_f32_e32 v200, v200, v79
	v_cvt_pk_bf16_f32 v236, v64, v65
	v_cvt_pk_bf16_f32 v237, v66, v67
	v_cvt_pk_bf16_f32 v238, v68, v69
	v_cvt_pk_bf16_f32 v239, v70, v71
	v_cvt_pk_bf16_f32 v240, v72, v73
	v_cvt_pk_bf16_f32 v241, v74, v75
	v_cvt_pk_bf16_f32 v242, v76, v77
	v_cvt_pk_bf16_f32 v243, v78, v79
	v_mov_b32_e32 v68, v236
	v_mov_b32_e32 v69, v237
	v_mov_b32_e32 v70, v238
	v_mov_b32_e32 v71, v239
	v_mov_b32_e32 v64, v240
	v_mov_b32_e32 v65, v241
	v_mov_b32_e32 v66, v242
	v_mov_b32_e32 v67, v243
	s_branch .LBB0_1332
.Lat_idle0:
	s_cmp_lg_u32 s55, 0
	s_cbranch_scc1 .Lat_idle_go0
	s_mov_b32 s55, 1
	v_exp_f32_e32 v64, v64
	v_exp_f32_e32 v65, v65
	v_add_f32_e32 v200, v200, v64
	v_exp_f32_e32 v66, v66
	v_add_f32_e32 v200, v200, v65
	v_exp_f32_e32 v67, v67
	v_add_f32_e32 v200, v200, v66
	v_exp_f32_e32 v68, v68
	v_add_f32_e32 v200, v200, v67
	v_exp_f32_e32 v69, v69
	v_add_f32_e32 v200, v200, v68
	v_exp_f32_e32 v70, v70
	v_add_f32_e32 v200, v200, v69
	v_exp_f32_e32 v71, v71
	v_add_f32_e32 v200, v200, v70
	v_exp_f32_e32 v72, v72
	v_add_f32_e32 v200, v200, v71
	v_exp_f32_e32 v73, v73
	v_add_f32_e32 v200, v200, v72
	v_exp_f32_e32 v74, v74
	v_add_f32_e32 v200, v200, v73
	v_exp_f32_e32 v75, v75
	v_add_f32_e32 v200, v200, v74
	v_exp_f32_e32 v76, v76
	v_add_f32_e32 v200, v200, v75
	v_exp_f32_e32 v77, v77
	v_add_f32_e32 v200, v200, v76
	v_exp_f32_e32 v78, v78
	v_add_f32_e32 v200, v200, v77
	v_exp_f32_e32 v79, v79
	v_add_f32_e32 v200, v200, v78
	v_add_f32_e32 v200, v200, v79
	v_cvt_pk_bf16_f32 v64, v64, v65
	v_cvt_pk_bf16_f32 v65, v66, v67
	v_cvt_pk_bf16_f32 v66, v68, v69
	v_cvt_pk_bf16_f32 v67, v70, v71
	v_cvt_pk_bf16_f32 v68, v72, v73
	v_cvt_pk_bf16_f32 v69, v74, v75
	v_cvt_pk_bf16_f32 v70, v76, v77
	v_cvt_pk_bf16_f32 v71, v78, v79
	ds_read_b128 v[164:167], v144 offset:49152
	ds_read_b128 v[168:171], v144 offset:53248
	ds_read_b128 v[176:179], v144 offset:57344
	ds_read_b128 v[226:229], v144 offset:61440
	s_waitcnt lgkmcnt(0)
	v_mfma_f32_32x32x16_bf16 v[48:63], v[164:167], v[64:67], v[48:63]
	v_mfma_f32_32x32x16_bf16 v[32:47], v[168:171], v[64:67], v[32:47]
	v_mfma_f32_32x32x16_bf16 v[16:31], v[176:179], v[64:67], v[16:31]
	v_mfma_f32_32x32x16_bf16 v[0:15], v[226:229], v[64:67], v[0:15]
	ds_read_b128 v[164:167], v145 offset:49152
	ds_read_b128 v[168:171], v145 offset:53248
	ds_read_b128 v[176:179], v145 offset:57344
	ds_read_b128 v[226:229], v145 offset:61440
	s_waitcnt lgkmcnt(0)
	v_mfma_f32_32x32x16_bf16 v[48:63], v[164:167], v[68:71], v[48:63]
	v_mfma_f32_32x32x16_bf16 v[32:47], v[168:171], v[68:71], v[32:47]
	v_mfma_f32_32x32x16_bf16 v[16:31], v[176:179], v[68:71], v[16:31]
	v_mfma_f32_32x32x16_bf16 v[0:15], v[226:229], v[68:71], v[0:15]
	s_nop 7
	v_mov_b32_e32 v64, 0xff61b1e6
	v_mov_b32_e32 v65, v64
	v_mov_b32_e32 v66, v64
	v_mov_b32_e32 v67, v64
	v_mov_b32_e32 v68, v64
	v_mov_b32_e32 v69, v64
	v_mov_b32_e32 v70, v64
	v_mov_b32_e32 v71, v64
	v_mov_b32_e32 v72, v64
	v_mov_b32_e32 v73, v64
	v_mov_b32_e32 v74, v64
	v_mov_b32_e32 v75, v64
	v_mov_b32_e32 v76, v64
	v_mov_b32_e32 v77, v64
	v_mov_b32_e32 v78, v64
	v_mov_b32_e32 v79, v64

.Lat_resc_a0:
	ds_bpermute_b32 v175, v246, v172
	s_waitcnt lgkmcnt(0)
	v_max3_f32 v175, v172, v175, s26
	v_exp_f32_e64 v172, -v175
	s_mov_b32 s54, 0x41000000
	s_mov_b32 s26, 0
	v_sub_f32_e32 v230, v230, v175
	v_sub_f32_e32 v231, v231, v175
	v_sub_f32_e32 v232, v232, v175
	v_sub_f32_e32 v233, v233, v175
	v_sub_f32_e32 v234, v234, v175
	v_sub_f32_e32 v235, v235, v175
	v_sub_f32_e32 v236, v236, v175
	v_sub_f32_e32 v237, v237, v175
	v_sub_f32_e32 v238, v238, v175
	v_sub_f32_e32 v239, v239, v175
	v_sub_f32_e32 v240, v240, v175
	v_sub_f32_e32 v241, v241, v175
	v_sub_f32_e32 v242, v242, v175
	v_sub_f32_e32 v243, v243, v175
	v_sub_f32_e32 v244, v244, v175
	v_sub_f32_e32 v245, v245, v175
	v_sub_f32_e32 v80, v80, v175
	v_sub_f32_e32 v81, v81, v175
	v_sub_f32_e32 v82, v82, v175
	v_sub_f32_e32 v83, v83, v175
	v_sub_f32_e32 v84, v84, v175
	v_sub_f32_e32 v85, v85, v175
	v_sub_f32_e32 v86, v86, v175
	v_sub_f32_e32 v87, v87, v175
	v_sub_f32_e32 v88, v88, v175
	v_sub_f32_e32 v89, v89, v175
	v_sub_f32_e32 v90, v90, v175
	v_sub_f32_e32 v91, v91, v175
	v_sub_f32_e32 v92, v92, v175
	v_sub_f32_e32 v93, v93, v175
	v_sub_f32_e32 v94, v94, v175
	v_sub_f32_e32 v95, v95, v175
	v_mul_f32_e32 v200, v200, v172
	s_nop 15
	s_nop 3
	v_mul_f32_e32 v0, v172, v0
	v_mul_f32_e32 v1, v172, v1
	v_mul_f32_e32 v2, v172, v2
	v_mul_f32_e32 v3, v172, v3
	v_mul_f32_e32 v4, v172, v4
	v_mul_f32_e32 v5, v172, v5
	v_mul_f32_e32 v6, v172, v6
	v_mul_f32_e32 v7, v172, v7
	v_mul_f32_e32 v8, v172, v8
	v_mul_f32_e32 v9, v172, v9
	v_mul_f32_e32 v10, v172, v10
	v_mul_f32_e32 v11, v172, v11
	v_mul_f32_e32 v12, v172, v12
	v_mul_f32_e32 v13, v172, v13
	v_mul_f32_e32 v14, v172, v14
	v_mul_f32_e32 v15, v172, v15
	v_mul_f32_e32 v16, v172, v16
	v_mul_f32_e32 v17, v172, v17
	v_mul_f32_e32 v18, v172, v18
	v_mul_f32_e32 v19, v172, v19
	v_mul_f32_e32 v20, v172, v20
	v_mul_f32_e32 v21, v172, v21
	v_mul_f32_e32 v22, v172, v22
	v_mul_f32_e32 v23, v172, v23
	v_mul_f32_e32 v24, v172, v24
	v_mul_f32_e32 v25, v172, v25
	v_mul_f32_e32 v26, v172, v26
	v_mul_f32_e32 v27, v172, v27
	v_mul_f32_e32 v28, v172, v28
	v_mul_f32_e32 v29, v172, v29
	v_mul_f32_e32 v30, v172, v30
	v_mul_f32_e32 v31, v172, v31
	v_mul_f32_e32 v32, v172, v32
	v_mul_f32_e32 v33, v172, v33
	v_mul_f32_e32 v34, v172, v34
	v_mul_f32_e32 v35, v172, v35
	v_mul_f32_e32 v36, v172, v36
	v_mul_f32_e32 v37, v172, v37
	v_mul_f32_e32 v38, v172, v38
	v_mul_f32_e32 v39, v172, v39
	v_mul_f32_e32 v40, v172, v40
	v_mul_f32_e32 v41, v172, v41
	v_mul_f32_e32 v42, v172, v42
	v_mul_f32_e32 v43, v172, v43
	v_mul_f32_e32 v44, v172, v44
	v_mul_f32_e32 v45, v172, v45
	v_mul_f32_e32 v46, v172, v46
	v_mul_f32_e32 v47, v172, v47
	v_mul_f32_e32 v48, v172, v48
	v_mul_f32_e32 v49, v172, v49
	v_mul_f32_e32 v50, v172, v50
	v_mul_f32_e32 v51, v172, v51
	v_mul_f32_e32 v52, v172, v52
	v_mul_f32_e32 v53, v172, v53
	v_mul_f32_e32 v54, v172, v54
	v_mul_f32_e32 v55, v172, v55
	v_mul_f32_e32 v56, v172, v56
	v_mul_f32_e32 v57, v172, v57
	v_mul_f32_e32 v58, v172, v58
	v_mul_f32_e32 v59, v172, v59
	v_mul_f32_e32 v60, v172, v60
	v_mul_f32_e32 v61, v172, v61
	v_mul_f32_e32 v62, v172, v62
	v_mul_f32_e32 v63, v172, v63
	s_branch .Lat_resc_a0_ret
.Lat_resc_b0:
	ds_bpermute_b32 v175, v246, v172
	s_waitcnt lgkmcnt(0)
	v_max3_f32 v175, v172, v175, s26
	v_exp_f32_e64 v172, -v175
	s_mov_b32 s54, 0x41000000
	s_mov_b32 s26, 0
	v_sub_f32_e32 v230, v230, v175
	v_sub_f32_e32 v231, v231, v175
	v_sub_f32_e32 v232, v232, v175
	v_sub_f32_e32 v233, v233, v175
	v_sub_f32_e32 v234, v234, v175
	v_sub_f32_e32 v235, v235, v175
	v_sub_f32_e32 v236, v236, v175
	v_sub_f32_e32 v237, v237, v175
	v_sub_f32_e32 v238, v238, v175
	v_sub_f32_e32 v239, v239, v175
	v_sub_f32_e32 v240, v240, v175
	v_sub_f32_e32 v241, v241, v175
	v_sub_f32_e32 v242, v242, v175
	v_sub_f32_e32 v243, v243, v175
	v_sub_f32_e32 v244, v244, v175
	v_sub_f32_e32 v245, v245, v175
	v_sub_f32_e32 v64, v64, v175
	v_sub_f32_e32 v65, v65, v175
	v_sub_f32_e32 v66, v66, v175
	v_sub_f32_e32 v67, v67, v175
	v_sub_f32_e32 v68, v68, v175
	v_sub_f32_e32 v69, v69, v175
	v_sub_f32_e32 v70, v70, v175
	v_sub_f32_e32 v71, v71, v175
	v_sub_f32_e32 v72, v72, v175
	v_sub_f32_e32 v73, v73, v175
	v_sub_f32_e32 v74, v74, v175
	v_sub_f32_e32 v75, v75, v175
	v_sub_f32_e32 v76, v76, v175
	v_sub_f32_e32 v77, v77, v175
	v_sub_f32_e32 v78, v78, v175
	v_sub_f32_e32 v79, v79, v175
	v_mul_f32_e32 v200, v200, v172
	s_nop 15
	s_nop 3
	v_mul_f32_e32 v0, v172, v0
	v_mul_f32_e32 v1, v172, v1
	v_mul_f32_e32 v2, v172, v2
	v_mul_f32_e32 v3, v172, v3
	v_mul_f32_e32 v4, v172, v4
	v_mul_f32_e32 v5, v172, v5
	v_mul_f32_e32 v6, v172, v6
	v_mul_f32_e32 v7, v172, v7
	v_mul_f32_e32 v8, v172, v8
	v_mul_f32_e32 v9, v172, v9
	v_mul_f32_e32 v10, v172, v10
	v_mul_f32_e32 v11, v172, v11
	v_mul_f32_e32 v12, v172, v12
	v_mul_f32_e32 v13, v172, v13
	v_mul_f32_e32 v14, v172, v14
	v_mul_f32_e32 v15, v172, v15
	v_mul_f32_e32 v16, v172, v16
	v_mul_f32_e32 v17, v172, v17
	v_mul_f32_e32 v18, v172, v18
	v_mul_f32_e32 v19, v172, v19
	v_mul_f32_e32 v20, v172, v20
	v_mul_f32_e32 v21, v172, v21
	v_mul_f32_e32 v22, v172, v22
	v_mul_f32_e32 v23, v172, v23
	v_mul_f32_e32 v24, v172, v24
	v_mul_f32_e32 v25, v172, v25
	v_mul_f32_e32 v26, v172, v26
	v_mul_f32_e32 v27, v172, v27
	v_mul_f32_e32 v28, v172, v28
	v_mul_f32_e32 v29, v172, v29
	v_mul_f32_e32 v30, v172, v30
	v_mul_f32_e32 v31, v172, v31
	v_mul_f32_e32 v32, v172, v32
	v_mul_f32_e32 v33, v172, v33
	v_mul_f32_e32 v34, v172, v34
	v_mul_f32_e32 v35, v172, v35
	v_mul_f32_e32 v36, v172, v36
	v_mul_f32_e32 v37, v172, v37
	v_mul_f32_e32 v38, v172, v38
	v_mul_f32_e32 v39, v172, v39
	v_mul_f32_e32 v40, v172, v40
	v_mul_f32_e32 v41, v172, v41
	v_mul_f32_e32 v42, v172, v42
	v_mul_f32_e32 v43, v172, v43
	v_mul_f32_e32 v44, v172, v44
	v_mul_f32_e32 v45, v172, v45
	v_mul_f32_e32 v46, v172, v46
	v_mul_f32_e32 v47, v172, v47
	v_mul_f32_e32 v48, v172, v48
	v_mul_f32_e32 v49, v172, v49
	v_mul_f32_e32 v50, v172, v50
	v_mul_f32_e32 v51, v172, v51
	v_mul_f32_e32 v52, v172, v52
	v_mul_f32_e32 v53, v172, v53
	v_mul_f32_e32 v54, v172, v54
	v_mul_f32_e32 v55, v172, v55
	v_mul_f32_e32 v56, v172, v56
	v_mul_f32_e32 v57, v172, v57
	v_mul_f32_e32 v58, v172, v58
	v_mul_f32_e32 v59, v172, v59
	v_mul_f32_e32 v60, v172, v60
	v_mul_f32_e32 v61, v172, v61
	v_mul_f32_e32 v62, v172, v62
	v_mul_f32_e32 v63, v172, v63
	s_branch .Lat_resc_b0_ret
.Lat_idle1:
	s_cmp_lg_u32 s55, 0
	s_cbranch_scc1 .Lat_idle_go1
	s_mov_b32 s55, 1
	v_exp_f32_e32 v64, v64
	v_exp_f32_e32 v65, v65
	v_add_f32_e32 v200, v200, v64
	v_exp_f32_e32 v66, v66
	v_add_f32_e32 v200, v200, v65
	v_exp_f32_e32 v67, v67
	v_add_f32_e32 v200, v200, v66
	v_exp_f32_e32 v68, v68
	v_add_f32_e32 v200, v200, v67
	v_exp_f32_e32 v69, v69
	v_add_f32_e32 v200, v200, v68
	v_exp_f32_e32 v70, v70
	v_add_f32_e32 v200, v200, v69
	v_exp_f32_e32 v71, v71
	v_add_f32_e32 v200, v200, v70
	v_exp_f32_e32 v72, v72
	v_add_f32_e32 v200, v200, v71
	v_exp_f32_e32 v73, v73
	v_add_f32_e32 v200, v200, v72
	v_exp_f32_e32 v74, v74
	v_add_f32_e32 v200, v200, v73
	v_exp_f32_e32 v75, v75
	v_add_f32_e32 v200, v200, v74
	v_exp_f32_e32 v76, v76
	v_add_f32_e32 v200, v200, v75
	v_exp_f32_e32 v77, v77
	v_add_f32_e32 v200, v200, v76
	v_exp_f32_e32 v78, v78
	v_add_f32_e32 v200, v200, v77
	v_exp_f32_e32 v79, v79
	v_add_f32_e32 v200, v200, v78
	v_add_f32_e32 v200, v200, v79
	v_cvt_pk_bf16_f32 v64, v64, v65
	v_cvt_pk_bf16_f32 v65, v66, v67
	v_cvt_pk_bf16_f32 v66, v68, v69
	v_cvt_pk_bf16_f32 v67, v70, v71
	v_cvt_pk_bf16_f32 v68, v72, v73
	v_cvt_pk_bf16_f32 v69, v74, v75
	v_cvt_pk_bf16_f32 v70, v76, v77
	v_cvt_pk_bf16_f32 v71, v78, v79
	ds_read_b128 v[164:167], v144
	ds_read_b128 v[168:171], v144 offset:4096
	ds_read_b128 v[176:179], v144 offset:8192
	ds_read_b128 v[226:229], v144 offset:12288
	s_waitcnt lgkmcnt(0)
	v_mfma_f32_32x32x16_bf16 v[48:63], v[164:167], v[64:67], v[48:63]
	v_mfma_f32_32x32x16_bf16 v[32:47], v[168:171], v[64:67], v[32:47]
	v_mfma_f32_32x32x16_bf16 v[16:31], v[176:179], v[64:67], v[16:31]
	v_mfma_f32_32x32x16_bf16 v[0:15], v[226:229], v[64:67], v[0:15]
	ds_read_b128 v[164:167], v145
	ds_read_b128 v[168:171], v145 offset:4096
	ds_read_b128 v[176:179], v145 offset:8192
	ds_read_b128 v[226:229], v145 offset:12288
	s_waitcnt lgkmcnt(0)
	v_mfma_f32_32x32x16_bf16 v[48:63], v[164:167], v[68:71], v[48:63]
	v_mfma_f32_32x32x16_bf16 v[32:47], v[168:171], v[68:71], v[32:47]
	v_mfma_f32_32x32x16_bf16 v[16:31], v[176:179], v[68:71], v[16:31]
	v_mfma_f32_32x32x16_bf16 v[0:15], v[226:229], v[68:71], v[0:15]
	s_nop 7
	v_mov_b32_e32 v64, 0xff61b1e6
	v_mov_b32_e32 v65, v64
	v_mov_b32_e32 v66, v64
	v_mov_b32_e32 v67, v64
	v_mov_b32_e32 v68, v64
	v_mov_b32_e32 v69, v64
	v_mov_b32_e32 v70, v64
	v_mov_b32_e32 v71, v64
	v_mov_b32_e32 v72, v64
	v_mov_b32_e32 v73, v64
	v_mov_b32_e32 v74, v64
	v_mov_b32_e32 v75, v64
	v_mov_b32_e32 v76, v64
	v_mov_b32_e32 v77, v64
	v_mov_b32_e32 v78, v64
	v_mov_b32_e32 v79, v64

.Lat_idle2:
	s_cmp_lg_u32 s55, 0
	s_cbranch_scc1 .Lat_idle_go2
	s_mov_b32 s55, 1
	v_exp_f32_e32 v64, v64
	v_exp_f32_e32 v65, v65
	v_add_f32_e32 v200, v200, v64
	v_exp_f32_e32 v66, v66
	v_add_f32_e32 v200, v200, v65
	v_exp_f32_e32 v67, v67
	v_add_f32_e32 v200, v200, v66
	v_exp_f32_e32 v68, v68
	v_add_f32_e32 v200, v200, v67
	v_exp_f32_e32 v69, v69
	v_add_f32_e32 v200, v200, v68
	v_exp_f32_e32 v70, v70
	v_add_f32_e32 v200, v200, v69
	v_exp_f32_e32 v71, v71
	v_add_f32_e32 v200, v200, v70
	v_exp_f32_e32 v72, v72
	v_add_f32_e32 v200, v200, v71
	v_exp_f32_e32 v73, v73
	v_add_f32_e32 v200, v200, v72
	v_exp_f32_e32 v74, v74
	v_add_f32_e32 v200, v200, v73
	v_exp_f32_e32 v75, v75
	v_add_f32_e32 v200, v200, v74
	v_exp_f32_e32 v76, v76
	v_add_f32_e32 v200, v200, v75
	v_exp_f32_e32 v77, v77
	v_add_f32_e32 v200, v200, v76
	v_exp_f32_e32 v78, v78
	v_add_f32_e32 v200, v200, v77
	v_exp_f32_e32 v79, v79
	v_add_f32_e32 v200, v200, v78
	v_add_f32_e32 v200, v200, v79
	v_cvt_pk_bf16_f32 v64, v64, v65
	v_cvt_pk_bf16_f32 v65, v66, v67
	v_cvt_pk_bf16_f32 v66, v68, v69
	v_cvt_pk_bf16_f32 v67, v70, v71
	v_cvt_pk_bf16_f32 v68, v72, v73
	v_cvt_pk_bf16_f32 v69, v74, v75
	v_cvt_pk_bf16_f32 v70, v76, v77
	v_cvt_pk_bf16_f32 v71, v78, v79
	ds_read_b128 v[164:167], v144 offset:16384
	ds_read_b128 v[168:171], v144 offset:20480
	ds_read_b128 v[176:179], v144 offset:24576
	ds_read_b128 v[226:229], v144 offset:28672
	s_waitcnt lgkmcnt(0)
	v_mfma_f32_32x32x16_bf16 v[48:63], v[164:167], v[64:67], v[48:63]
	v_mfma_f32_32x32x16_bf16 v[32:47], v[168:171], v[64:67], v[32:47]
	v_mfma_f32_32x32x16_bf16 v[16:31], v[176:179], v[64:67], v[16:31]
	v_mfma_f32_32x32x16_bf16 v[0:15], v[226:229], v[64:67], v[0:15]
	ds_read_b128 v[164:167], v145 offset:16384
	ds_read_b128 v[168:171], v145 offset:20480
	ds_read_b128 v[176:179], v145 offset:24576
	ds_read_b128 v[226:229], v145 offset:28672
	s_waitcnt lgkmcnt(0)
	v_mfma_f32_32x32x16_bf16 v[48:63], v[164:167], v[68:71], v[48:63]
	v_mfma_f32_32x32x16_bf16 v[32:47], v[168:171], v[68:71], v[32:47]
	v_mfma_f32_32x32x16_bf16 v[16:31], v[176:179], v[68:71], v[16:31]
	v_mfma_f32_32x32x16_bf16 v[0:15], v[226:229], v[68:71], v[0:15]
	s_nop 7
	v_mov_b32_e32 v64, 0xff61b1e6
	v_mov_b32_e32 v65, v64
	v_mov_b32_e32 v66, v64
	v_mov_b32_e32 v67, v64
	v_mov_b32_e32 v68, v64
	v_mov_b32_e32 v69, v64
	v_mov_b32_e32 v70, v64
	v_mov_b32_e32 v71, v64
	v_mov_b32_e32 v72, v64
	v_mov_b32_e32 v73, v64
	v_mov_b32_e32 v74, v64
	v_mov_b32_e32 v75, v64
	v_mov_b32_e32 v76, v64
	v_mov_b32_e32 v77, v64
	v_mov_b32_e32 v78, v64
	v_mov_b32_e32 v79, v64

.Lat_idle3:
	s_cmp_lg_u32 s55, 0
	s_cbranch_scc1 .Lat_idle_go3
	s_mov_b32 s55, 1
	v_exp_f32_e32 v64, v64
	v_exp_f32_e32 v65, v65
	v_add_f32_e32 v200, v200, v64
	v_exp_f32_e32 v66, v66
	v_add_f32_e32 v200, v200, v65
	v_exp_f32_e32 v67, v67
	v_add_f32_e32 v200, v200, v66
	v_exp_f32_e32 v68, v68
	v_add_f32_e32 v200, v200, v67
	v_exp_f32_e32 v69, v69
	v_add_f32_e32 v200, v200, v68
	v_exp_f32_e32 v70, v70
	v_add_f32_e32 v200, v200, v69
	v_exp_f32_e32 v71, v71
	v_add_f32_e32 v200, v200, v70
	v_exp_f32_e32 v72, v72
	v_add_f32_e32 v200, v200, v71
	v_exp_f32_e32 v73, v73
	v_add_f32_e32 v200, v200, v72
	v_exp_f32_e32 v74, v74
	v_add_f32_e32 v200, v200, v73
	v_exp_f32_e32 v75, v75
	v_add_f32_e32 v200, v200, v74
	v_exp_f32_e32 v76, v76
	v_add_f32_e32 v200, v200, v75
	v_exp_f32_e32 v77, v77
	v_add_f32_e32 v200, v200, v76
	v_exp_f32_e32 v78, v78
	v_add_f32_e32 v200, v200, v77
	v_exp_f32_e32 v79, v79
	v_add_f32_e32 v200, v200, v78
	v_add_f32_e32 v200, v200, v79
	v_cvt_pk_bf16_f32 v64, v64, v65
	v_cvt_pk_bf16_f32 v65, v66, v67
	v_cvt_pk_bf16_f32 v66, v68, v69
	v_cvt_pk_bf16_f32 v67, v70, v71
	v_cvt_pk_bf16_f32 v68, v72, v73
	v_cvt_pk_bf16_f32 v69, v74, v75
	v_cvt_pk_bf16_f32 v70, v76, v77
	v_cvt_pk_bf16_f32 v71, v78, v79
	ds_read_b128 v[164:167], v144 offset:32768
	ds_read_b128 v[168:171], v144 offset:36864
	ds_read_b128 v[176:179], v144 offset:40960
	ds_read_b128 v[226:229], v144 offset:45056
	s_waitcnt lgkmcnt(0)
	v_mfma_f32_32x32x16_bf16 v[48:63], v[164:167], v[64:67], v[48:63]
	v_mfma_f32_32x32x16_bf16 v[32:47], v[168:171], v[64:67], v[32:47]
	v_mfma_f32_32x32x16_bf16 v[16:31], v[176:179], v[64:67], v[16:31]
	v_mfma_f32_32x32x16_bf16 v[0:15], v[226:229], v[64:67], v[0:15]
	ds_read_b128 v[164:167], v145 offset:32768
	ds_read_b128 v[168:171], v145 offset:36864
	ds_read_b128 v[176:179], v145 offset:40960
	ds_read_b128 v[226:229], v145 offset:45056
	s_waitcnt lgkmcnt(0)
	v_mfma_f32_32x32x16_bf16 v[48:63], v[164:167], v[68:71], v[48:63]
	v_mfma_f32_32x32x16_bf16 v[32:47], v[168:171], v[68:71], v[32:47]
	v_mfma_f32_32x32x16_bf16 v[16:31], v[176:179], v[68:71], v[16:31]
	v_mfma_f32_32x32x16_bf16 v[0:15], v[226:229], v[68:71], v[0:15]
	s_nop 7
	v_mov_b32_e32 v64, 0xff61b1e6
	v_mov_b32_e32 v65, v64
	v_mov_b32_e32 v66, v64
	v_mov_b32_e32 v67, v64
	v_mov_b32_e32 v68, v64
	v_mov_b32_e32 v69, v64
	v_mov_b32_e32 v70, v64
	v_mov_b32_e32 v71, v64
	v_mov_b32_e32 v72, v64
	v_mov_b32_e32 v73, v64
	v_mov_b32_e32 v74, v64
	v_mov_b32_e32 v75, v64
	v_mov_b32_e32 v76, v64
	v_mov_b32_e32 v77, v64
	v_mov_b32_e32 v78, v64
	v_mov_b32_e32 v79, v64
